# cross-attn K/V staging batched + Q double-buffer; RESID epilogue all residual loads up front; indexer relu trim
# speedup vs baseline: 1.0219x; 1.0219x over previous
; DI f32x16 mfma32(bf16x8 a, bf16x8 b, f32x16 c) { return __builtin_amdgcn_mfma_f32_32x32x16_bf16(a, b, c, 0, 0, 0); }
; DI f32x16 zero16() { f32x16 z; for (int i = 0; i < 16; ++i) z[i] = 0.f; return z; }
; DI void dsa_item(const Params& P0_, int b, int item, uchar* smem) {
;     ...
;     for (int c = wave; c < nkt; c += 4) {
;       bf16x8 n0f = k0f, n1f = k1f, n2f = k2f, n3f = k3f;
;       if (c + 4 < nkt) {
;         const u16* krow = KIF + ((size_t)((tokbase >> 5) + c + 4) * 256 + lane) * 8;
;         n0f = *(const bf16x8*)(krow); n1f = *(const bf16x8*)(krow + 512); n2f = *(const bf16x8*)(krow + 1024); n3f = *(const bf16x8*)(krow + 1536);
;       }
;       f32x16 a = zero16();
;       a = mfma32(af[0], k0f, a); a = mfma32(af[1], k1f, a); a = mfma32(af[2], k2f, a); a = mfma32(af[3], k3f, a);
;       float sa = 0.f, sb = 0.f;
; #pragma unroll
;       for (int i = 0; i < 8; ++i) { sa += fmaxf(a[i], 0.f) * wa[i]; sb += fmaxf(a[8 + i], 0.f) * wb[i]; }
;       sc[h * 4096 + 32 * c + r31] = sa;
;       sc[(h + 2) * 4096 + 32 * c + r31] = sb;
;       k0f = n0f; k1f = n1f; k2f = n2f; k3f = n3f;
;     }
.LBB0_268:
	s_or_b64 exec, exec, s[10:11]
	v_mfma_f32_32x32x16_bf16 v[2:17], v[30:33], v[2:5], 0
	s_and_b64 s[0:1], exec, vcc
	s_or_b64 s[8:9], s[0:1], s[8:9]
	s_mov_b64 s[0:1], 0x4000
	v_lshl_add_u64 v[66:67], v[66:67], 0, s[0:1]
	v_mfma_f32_32x32x16_bf16 v[2:17], v[26:29], v[58:61], v[2:17]
	v_mfma_f32_32x32x16_bf16 v[2:17], v[22:25], v[54:57], v[2:17]
	v_mfma_f32_32x32x16_bf16 v[2:17], v[18:21], v[50:53], v[2:17]
	s_nop 11
	v_max_f32_e32 v10, 0, v10
	v_max_f32_e32 v2, 0, v2
	v_max_f32_e32 v11, 0, v11
	v_fma_f32 v10, v10, v75, 0
	v_max_f32_e32 v3, 0, v3
	v_max_f32_e32 v12, 0, v12
	v_fma_f32 v2, v2, v0, 0
	v_fmac_f32_e32 v10, v11, v76
	v_max_f32_e32 v4, 0, v4
	v_max_f32_e32 v13, 0, v13
	v_fmac_f32_e32 v2, v3, v68
	v_fmac_f32_e32 v10, v12, v77
	v_max_f32_e32 v5, 0, v5
	v_max_f32_e32 v14, 0, v14
	v_fmac_f32_e32 v2, v4, v69
	v_fmac_f32_e32 v10, v13, v78
	v_max_f32_e32 v6, 0, v6
	v_fmac_f32_e32 v2, v5, v70
	v_fmac_f32_e32 v10, v14, v79
	v_max_f32_e32 v3, 0, v15
	v_max_f32_e32 v7, 0, v7
	v_fmac_f32_e32 v2, v6, v71
	v_fmac_f32_e32 v10, v3, v80
	v_fmac_f32_e32 v2, v7, v72
	v_max_f32_e32 v3, 0, v8
	v_fmac_f32_e32 v2, v3, v73
	v_max_f32_e32 v3, 0, v16
	v_fmac_f32_e32 v10, v3, v81
	v_max_f32_e32 v3, 0, v9
	v_fmac_f32_e32 v2, v3, v74
	v_max_f32_e32 v3, 0, v17
	v_fmac_f32_e32 v10, v3, v82
	ds_write2st64_b32 v65, v2, v10 offset1:128
	s_waitcnt vmcnt(0)
	v_mov_b64_e32 v[60:61], v[44:45]
	v_mov_b64_e32 v[58:59], v[42:43]
	v_mov_b64_e32 v[56:57], v[40:41]
	v_mov_b64_e32 v[54:55], v[38:39]
	v_mov_b64_e32 v[52:53], v[36:37]
	v_mov_b64_e32 v[50:51], v[34:35]
	v_mov_b64_e32 v[2:3], v[46:47]
	v_add_u32_e32 v65, 0x200, v65
	v_mov_b64_e32 v[4:5], v[48:49]
	s_andn2_b64 exec, exec, s[8:9]
	s_cbranch_execz .LBB0_271

.LBB0_1326:
	v_add_u32_e32 v131, s12, v130
	v_ashrrev_i32_e32 v0, 7, v131
	v_and_or_b32 v0, v0, -8, v141
	v_lshl_add_u32 v133, v0, 4, v142
	v_lshl_add_u32 v0, v0, 2, s38
	v_ashrrev_i32_e32 v136, 5, v0
	v_ashrrev_i32_e32 v137, 31, v136
	v_lshlrev_b64 v[136:137], 21, v[136:137]
	v_lshl_add_u64 v[136:137], v[134:135], 0, v[136:137]
	v_lshlrev_b32_e32 v0, 3, v141
	v_lshl_add_u64 v[136:137], v[136:137], 0, v[0:1]
	s_and_b32 s32, s12, 0xfff
	s_cbranch_scc1 .Lrx_skip12
	global_load_dwordx2 v[170:171], v[136:137], off
	global_load_dwordx2 v[172:173], v[136:137], off offset:2048
	s_mov_b64 s[100:101], 0x1000
	v_lshl_add_u64 v[174:175], v[136:137], 0, s[100:101]
	global_load_dwordx2 v[176:177], v[174:175], off offset:2048
	global_load_dwordx2 v[174:175], v[174:175], off
	s_mov_b64 s[100:101], 0x200000
	v_lshl_add_u64 v[178:179], v[136:137], 0, s[100:101]
	s_mov_b64 s[100:101], 0x201000
	v_lshl_add_u64 v[182:183], v[136:137], 0, s[100:101]
	global_load_dwordx2 v[180:181], v[178:179], off offset:2048
	global_load_dwordx2 v[178:179], v[178:179], off
	global_load_dwordx2 v[184:185], v[182:183], off offset:2048
	global_load_dwordx2 v[182:183], v[182:183], off
	s_mov_b64 s[100:101], 0x400000
	v_lshl_add_u64 v[186:187], v[136:137], 0, s[100:101]
	s_mov_b64 s[100:101], 0x401000
	v_lshl_add_u64 v[190:191], v[136:137], 0, s[100:101]
	global_load_dwordx2 v[188:189], v[186:187], off offset:2048
	global_load_dwordx2 v[186:187], v[186:187], off
	global_load_dwordx2 v[192:193], v[190:191], off offset:2048
	global_load_dwordx2 v[190:191], v[190:191], off
	s_mov_b64 s[100:101], 0x600000
	v_lshl_add_u64 v[194:195], v[136:137], 0, s[100:101]
	s_mov_b64 s[100:101], 0x601000
	v_lshl_add_u64 v[198:199], v[136:137], 0, s[100:101]
	global_load_dwordx2 v[196:197], v[194:195], off offset:2048
	global_load_dwordx2 v[194:195], v[194:195], off
	global_load_dwordx2 v[200:201], v[198:199], off offset:2048
	global_load_dwordx2 v[198:199], v[198:199], off
	s_waitcnt vmcnt(0)
.Lrx_skip12:
	s_addk_i32 s12, 0x400
	s_cmpk_eq_i32 s12, 0x1000
	v_mov_b64_e32 v[136:137], v[170:171]
	v_lshlrev_b32_e32 v146, 16, v136
	v_and_b32_e32 v147, 0xffff0000, v136
	v_lshlrev_b32_e32 v148, 16, v137
	v_and_b32_e32 v149, 0xffff0000, v137
	ds_read_b128 v[136:139], v133
	s_waitcnt lgkmcnt(0)
	v_pk_fma_f32 v[136:137], v[146:147], s[2:3], v[136:137] op_sel_hi:[1,0,1]
	v_pk_fma_f32 v[138:139], v[148:149], s[2:3], v[138:139] op_sel_hi:[1,0,1]
	ds_write_b128 v133, v[136:139]
	v_add_u32_e32 v133, 0x100, v131
	v_bfe_u32 v136, v133, 3, 7
	v_ashrrev_i32_e32 v133, 7, v133
	v_and_or_b32 v133, v133, -8, v141
	v_lshlrev_b32_e32 v137, 4, v133
	v_lshl_add_u32 v133, v133, 2, s38
	v_mad_u32_u24 v150, v136, s94, v137
	v_or_b32_e32 v138, s39, v136
	v_ashrrev_i32_e32 v136, 5, v133
	v_ashrrev_i32_e32 v137, 31, v136
	v_lshlrev_b64 v[136:137], 21, v[136:137]
	v_lshl_add_u64 v[136:137], s[90:91], 0, v[136:137]
	v_lshlrev_b32_e32 v138, 6, v138
	v_mov_b32_e32 v139, v1
	v_lshl_add_u64 v[136:137], v[136:137], 0, v[138:139]
	v_lshl_add_u64 v[136:137], v[136:137], 0, v[0:1]
	v_add_u32_e32 v133, 0x200, v131
	v_add_u32_e32 v131, 0x300, v131
	v_mov_b64_e32 v[136:137], v[172:173]
	v_lshlrev_b32_e32 v146, 16, v136
	v_and_b32_e32 v147, 0xffff0000, v136
	v_lshlrev_b32_e32 v148, 16, v137
	v_and_b32_e32 v149, 0xffff0000, v137
	ds_read_b128 v[136:139], v150
	s_waitcnt lgkmcnt(0)
	v_pk_fma_f32 v[136:137], v[146:147], s[2:3], v[136:137] op_sel_hi:[1,0,1]
	v_pk_fma_f32 v[138:139], v[148:149], s[2:3], v[138:139] op_sel_hi:[1,0,1]
	ds_write_b128 v150, v[136:139]
	v_bfe_u32 v136, v133, 3, 7
	v_ashrrev_i32_e32 v133, 7, v133
	v_and_or_b32 v133, v133, -8, v141
	v_lshlrev_b32_e32 v137, 4, v133
	v_lshl_add_u32 v133, v133, 2, s38
	v_mad_u32_u24 v150, v136, s94, v137
	v_or_b32_e32 v138, s39, v136
	v_ashrrev_i32_e32 v136, 5, v133
	v_ashrrev_i32_e32 v137, 31, v136
	v_lshlrev_b64 v[136:137], 21, v[136:137]
	v_lshl_add_u64 v[136:137], s[90:91], 0, v[136:137]
	v_lshlrev_b32_e32 v138, 6, v138
	v_mov_b32_e32 v139, v1
	v_lshl_add_u64 v[136:137], v[136:137], 0, v[138:139]
	v_lshl_add_u64 v[136:137], v[136:137], 0, v[0:1]
	v_bfe_u32 v133, v131, 3, 7
	v_ashrrev_i32_e32 v131, 7, v131
	v_and_or_b32 v131, v131, -8, v141
	v_mov_b64_e32 v[136:137], v[174:175]
	v_lshlrev_b32_e32 v146, 16, v136
	v_and_b32_e32 v147, 0xffff0000, v136
	v_lshlrev_b32_e32 v148, 16, v137
	v_and_b32_e32 v149, 0xffff0000, v137
	ds_read_b128 v[136:139], v150
	s_waitcnt lgkmcnt(0)
	v_pk_fma_f32 v[136:137], v[146:147], s[2:3], v[136:137] op_sel_hi:[1,0,1]
	v_pk_fma_f32 v[138:139], v[148:149], s[2:3], v[138:139] op_sel_hi:[1,0,1]
	ds_write_b128 v150, v[136:139]
	v_lshlrev_b32_e32 v136, 4, v131
	v_lshl_add_u32 v131, v131, 2, s38
	v_mad_u32_u24 v150, v133, s94, v136
	v_ashrrev_i32_e32 v136, 5, v131
	v_ashrrev_i32_e32 v137, 31, v136
	v_or_b32_e32 v133, s39, v133
	v_lshlrev_b64 v[136:137], 21, v[136:137]
	v_lshl_add_u64 v[136:137], s[90:91], 0, v[136:137]
	v_lshlrev_b32_e32 v138, 6, v133
	v_mov_b32_e32 v139, v1
	v_lshl_add_u64 v[136:137], v[136:137], 0, v[138:139]
	v_lshl_add_u64 v[136:137], v[136:137], 0, v[0:1]
	v_mov_b64_e32 v[136:137], v[176:177]
	v_mov_b64_e32 v[170:171], v[178:179]
	v_mov_b64_e32 v[172:173], v[180:181]
	v_mov_b64_e32 v[174:175], v[182:183]
	v_mov_b64_e32 v[176:177], v[184:185]
	v_mov_b64_e32 v[178:179], v[186:187]
	v_mov_b64_e32 v[180:181], v[188:189]
	v_mov_b64_e32 v[182:183], v[190:191]
	v_mov_b64_e32 v[184:185], v[192:193]
	v_mov_b64_e32 v[186:187], v[194:195]
	v_mov_b64_e32 v[188:189], v[196:197]
	v_mov_b64_e32 v[190:191], v[198:199]
	v_mov_b64_e32 v[192:193], v[200:201]
	v_lshlrev_b32_e32 v146, 16, v136
	v_and_b32_e32 v147, 0xffff0000, v136
	v_lshlrev_b32_e32 v148, 16, v137
	v_and_b32_e32 v149, 0xffff0000, v137
	ds_read_b128 v[136:139], v150
	s_waitcnt lgkmcnt(0)
	v_pk_fma_f32 v[136:137], v[146:147], s[2:3], v[136:137] op_sel_hi:[1,0,1]
	v_pk_fma_f32 v[138:139], v[148:149], s[2:3], v[138:139] op_sel_hi:[1,0,1]
	ds_write_b128 v150, v[136:139]
	s_cbranch_scc0 .LBB0_1326
	s_lshl_b32 s13, s37, 8
	s_lshl_b32 s12, s39, 3
	s_and_b32 s13, s13, 0x700
	s_mov_b32 s15, s45
	s_or_b32 s14, s12, s13
	s_lshl_b64 s[14:15], s[14:15], 3
	s_add_u32 s14, s6, s14
	s_movk_i32 s13, 0x80
	s_addc_u32 s15, s7, s15
	v_cmp_gt_i32_e32 vcc, s13, v130
	v_mul_lo_u32 v133, v130, s94
	s_waitcnt lgkmcnt(0)
	s_barrier
	s_and_saveexec_b64 s[16:17], vcc
	s_cbranch_execz .LBB0_1331
	v_mov_b32_e32 v134, 0
	s_mov_b32 s13, 0
	v_mov_b32_e32 v135, v134

.LBB0_1334:
	v_add_u32_e32 v131, s13, v130
	v_ashrrev_i32_e32 v135, 7, v131
	v_and_or_b32 v135, v135, -8, v141
	v_lshl_add_u32 v152, v135, 4, v142
	v_lshl_add_u32 v135, v135, 2, s38
	v_ashrrev_i32_e32 v138, 5, v135
	v_ashrrev_i32_e32 v139, 31, v138
	v_lshlrev_b64 v[138:139], 21, v[138:139]
	v_lshl_add_u64 v[138:139], v[136:137], 0, v[138:139]
	v_lshl_add_u64 v[138:139], v[138:139], 0, v[0:1]
	s_and_b32 s32, s13, 0xfff
	s_cbranch_scc1 .Lrx_skip11
	global_load_dwordx2 v[170:171], v[138:139], off
	global_load_dwordx2 v[172:173], v[138:139], off offset:2048
	s_mov_b64 s[100:101], 0x1000
	v_lshl_add_u64 v[174:175], v[138:139], 0, s[100:101]
	global_load_dwordx2 v[176:177], v[174:175], off offset:2048
	global_load_dwordx2 v[174:175], v[174:175], off
	s_mov_b64 s[100:101], 0x200000
	v_lshl_add_u64 v[178:179], v[138:139], 0, s[100:101]
	s_mov_b64 s[100:101], 0x201000
	v_lshl_add_u64 v[182:183], v[138:139], 0, s[100:101]
	global_load_dwordx2 v[180:181], v[178:179], off offset:2048
	global_load_dwordx2 v[178:179], v[178:179], off
	global_load_dwordx2 v[184:185], v[182:183], off offset:2048
	global_load_dwordx2 v[182:183], v[182:183], off
	s_mov_b64 s[100:101], 0x400000
	v_lshl_add_u64 v[186:187], v[138:139], 0, s[100:101]
	s_mov_b64 s[100:101], 0x401000
	v_lshl_add_u64 v[190:191], v[138:139], 0, s[100:101]
	global_load_dwordx2 v[188:189], v[186:187], off offset:2048
	global_load_dwordx2 v[186:187], v[186:187], off
	global_load_dwordx2 v[192:193], v[190:191], off offset:2048
	global_load_dwordx2 v[190:191], v[190:191], off
	s_mov_b64 s[100:101], 0x600000
	v_lshl_add_u64 v[194:195], v[138:139], 0, s[100:101]
	s_mov_b64 s[100:101], 0x601000
	v_lshl_add_u64 v[198:199], v[138:139], 0, s[100:101]
	global_load_dwordx2 v[196:197], v[194:195], off offset:2048
	global_load_dwordx2 v[194:195], v[194:195], off
	global_load_dwordx2 v[200:201], v[198:199], off offset:2048
	global_load_dwordx2 v[198:199], v[198:199], off
	s_waitcnt vmcnt(0)
.Lrx_skip11:
	ds_read_b128 v[146:149], v152
	v_add_u32_e32 v135, 0x100, v131
	s_addk_i32 s13, 0x400
	s_cmpk_lg_i32 s13, 0x1000
	v_mov_b64_e32 v[138:139], v[170:171]
	v_lshlrev_b32_e32 v150, 16, v138
	v_and_b32_e32 v151, 0xffff0000, v138
	v_lshlrev_b32_e32 v138, 16, v139
	v_and_b32_e32 v139, 0xffff0000, v139
	s_waitcnt lgkmcnt(0)
	v_pk_fma_f32 v[148:149], v[138:139], s[2:3], v[148:149] op_sel_hi:[1,0,1]
	v_bfe_u32 v138, v135, 3, 7
	v_ashrrev_i32_e32 v135, 7, v135
	v_and_or_b32 v135, v135, -8, v141
	v_pk_fma_f32 v[146:147], v[150:151], s[2:3], v[146:147] op_sel_hi:[1,0,1]
	v_lshlrev_b32_e32 v139, 4, v135
	v_lshl_add_u32 v135, v135, 2, s38
	ds_write_b128 v152, v[146:149]
	v_mad_u32_u24 v152, v138, s94, v139
	v_or_b32_e32 v146, s40, v138
	v_ashrrev_i32_e32 v138, 5, v135
	v_ashrrev_i32_e32 v139, 31, v138
	v_lshlrev_b64 v[138:139], 21, v[138:139]
	v_lshl_add_u64 v[138:139], s[90:91], 0, v[138:139]
	v_lshlrev_b32_e32 v146, 6, v146
	v_mov_b32_e32 v147, v1
	v_lshl_add_u64 v[138:139], v[138:139], 0, v[146:147]
	v_lshl_add_u64 v[138:139], v[138:139], 0, v[0:1]
	ds_read_b128 v[146:149], v152
	v_add_u32_e32 v135, 0x200, v131
	v_add_u32_e32 v131, 0x300, v131
	v_mov_b64_e32 v[138:139], v[172:173]
	v_lshlrev_b32_e32 v150, 16, v138
	v_and_b32_e32 v151, 0xffff0000, v138
	v_lshlrev_b32_e32 v138, 16, v139
	v_and_b32_e32 v139, 0xffff0000, v139
	s_waitcnt lgkmcnt(0)
	v_pk_fma_f32 v[148:149], v[138:139], s[2:3], v[148:149] op_sel_hi:[1,0,1]
	v_bfe_u32 v138, v135, 3, 7
	v_ashrrev_i32_e32 v135, 7, v135
	v_and_or_b32 v135, v135, -8, v141
	v_pk_fma_f32 v[146:147], v[150:151], s[2:3], v[146:147] op_sel_hi:[1,0,1]
	v_lshlrev_b32_e32 v139, 4, v135
	v_lshl_add_u32 v135, v135, 2, s38
	ds_write_b128 v152, v[146:149]
	v_mad_u32_u24 v152, v138, s94, v139
	v_or_b32_e32 v146, s40, v138
	v_ashrrev_i32_e32 v138, 5, v135
	v_ashrrev_i32_e32 v139, 31, v138
	v_lshlrev_b64 v[138:139], 21, v[138:139]
	v_lshl_add_u64 v[138:139], s[90:91], 0, v[138:139]
	v_lshlrev_b32_e32 v146, 6, v146
	v_mov_b32_e32 v147, v1
	v_lshl_add_u64 v[138:139], v[138:139], 0, v[146:147]
	v_lshl_add_u64 v[138:139], v[138:139], 0, v[0:1]
	ds_read_b128 v[146:149], v152
	v_bfe_u32 v135, v131, 3, 7
	v_ashrrev_i32_e32 v131, 7, v131
	v_and_or_b32 v131, v131, -8, v141
	v_mov_b64_e32 v[138:139], v[174:175]
	v_lshlrev_b32_e32 v150, 16, v138
	v_and_b32_e32 v151, 0xffff0000, v138
	v_lshlrev_b32_e32 v138, 16, v139
	v_and_b32_e32 v139, 0xffff0000, v139
	s_waitcnt lgkmcnt(0)
	v_pk_fma_f32 v[146:147], v[150:151], s[2:3], v[146:147] op_sel_hi:[1,0,1]
	v_pk_fma_f32 v[148:149], v[138:139], s[2:3], v[148:149] op_sel_hi:[1,0,1]
	v_lshlrev_b32_e32 v138, 4, v131
	v_lshl_add_u32 v131, v131, 2, s38
	ds_write_b128 v152, v[146:149]
	v_mad_u32_u24 v152, v135, s94, v138
	v_ashrrev_i32_e32 v138, 5, v131
	v_ashrrev_i32_e32 v139, 31, v138
	v_or_b32_e32 v135, s40, v135
	v_lshlrev_b64 v[138:139], 21, v[138:139]
	v_lshl_add_u64 v[138:139], s[90:91], 0, v[138:139]
	v_lshlrev_b32_e32 v146, 6, v135
	v_mov_b32_e32 v147, v1
	v_lshl_add_u64 v[138:139], v[138:139], 0, v[146:147]
	v_lshl_add_u64 v[138:139], v[138:139], 0, v[0:1]
	ds_read_b128 v[146:149], v152
	v_mov_b64_e32 v[138:139], v[176:177]
	v_mov_b64_e32 v[170:171], v[178:179]
	v_mov_b64_e32 v[172:173], v[180:181]
	v_mov_b64_e32 v[174:175], v[182:183]
	v_mov_b64_e32 v[176:177], v[184:185]
	v_mov_b64_e32 v[178:179], v[186:187]
	v_mov_b64_e32 v[180:181], v[188:189]
	v_mov_b64_e32 v[182:183], v[190:191]
	v_mov_b64_e32 v[184:185], v[192:193]
	v_mov_b64_e32 v[186:187], v[194:195]
	v_mov_b64_e32 v[188:189], v[196:197]
	v_mov_b64_e32 v[190:191], v[198:199]
	v_mov_b64_e32 v[192:193], v[200:201]
	v_lshlrev_b32_e32 v150, 16, v138
	v_and_b32_e32 v151, 0xffff0000, v138
	v_lshlrev_b32_e32 v138, 16, v139
	v_and_b32_e32 v139, 0xffff0000, v139
	s_waitcnt lgkmcnt(0)
	v_pk_fma_f32 v[146:147], v[150:151], s[2:3], v[146:147] op_sel_hi:[1,0,1]
	v_pk_fma_f32 v[148:149], v[138:139], s[2:3], v[148:149] op_sel_hi:[1,0,1]
	ds_write_b128 v152, v[146:149]
	s_cbranch_scc1 .LBB0_1334
	s_waitcnt lgkmcnt(0)
	s_barrier
	s_and_saveexec_b64 s[16:17], vcc
	s_cbranch_execz .LBB0_1339
	v_mov_b32_e32 v136, 0
	s_mov_b32 s13, 0
	v_mov_b32_e32 v137, v136

.LBB0_1358:
	v_add_u32_e32 v131, s16, v130
	v_ashrrev_i32_e32 v135, 7, v131
	v_and_or_b32 v135, v135, -8, v141
	v_lshlrev_b32_e32 v146, 2, v135
	v_lshl_add_u32 v152, v135, 4, v142
	v_add_u32_e32 v135, s38, v146
	v_ashrrev_i32_e32 v148, 5, v135
	v_ashrrev_i32_e32 v149, 31, v148
	v_lshlrev_b64 v[148:149], 21, v[148:149]
	v_lshl_add_u64 v[148:149], v[132:133], 0, v[148:149]
	v_lshl_add_u64 v[158:159], v[148:149], 0, v[0:1]
	s_and_b32 s32, s16, 0xfff
	s_cbranch_scc1 .Lrx_skip10
	global_load_dwordx2 v[170:171], v[158:159], off
	global_load_dwordx2 v[172:173], v[158:159], off offset:2048
	s_mov_b64 s[100:101], 0x1000
	v_lshl_add_u64 v[174:175], v[158:159], 0, s[100:101]
	global_load_dwordx2 v[176:177], v[174:175], off offset:2048
	global_load_dwordx2 v[174:175], v[174:175], off
	s_mov_b64 s[100:101], 0x200000
	v_lshl_add_u64 v[178:179], v[158:159], 0, s[100:101]
	s_mov_b64 s[100:101], 0x201000
	v_lshl_add_u64 v[182:183], v[158:159], 0, s[100:101]
	global_load_dwordx2 v[180:181], v[178:179], off offset:2048
	global_load_dwordx2 v[178:179], v[178:179], off
	global_load_dwordx2 v[184:185], v[182:183], off offset:2048
	global_load_dwordx2 v[182:183], v[182:183], off
	s_mov_b64 s[100:101], 0x400000
	v_lshl_add_u64 v[186:187], v[158:159], 0, s[100:101]
	s_mov_b64 s[100:101], 0x401000
	v_lshl_add_u64 v[190:191], v[158:159], 0, s[100:101]
	global_load_dwordx2 v[188:189], v[186:187], off offset:2048
	global_load_dwordx2 v[186:187], v[186:187], off
	global_load_dwordx2 v[192:193], v[190:191], off offset:2048
	global_load_dwordx2 v[190:191], v[190:191], off
	s_mov_b64 s[100:101], 0x600000
	v_lshl_add_u64 v[194:195], v[158:159], 0, s[100:101]
	s_mov_b64 s[100:101], 0x601000
	v_lshl_add_u64 v[198:199], v[158:159], 0, s[100:101]
	global_load_dwordx2 v[196:197], v[194:195], off offset:2048
	global_load_dwordx2 v[194:195], v[194:195], off
	global_load_dwordx2 v[200:201], v[198:199], off offset:2048
	global_load_dwordx2 v[198:199], v[198:199], off
	s_waitcnt vmcnt(0)
.Lrx_skip10:
	v_ashrrev_i32_e32 v147, 31, v146
	v_lshlrev_b64 v[146:147], 2, v[146:147]
	v_lshl_add_u64 v[150:151], s[12:13], 0, v[146:147]
	v_lshl_add_u64 v[154:155], s[14:15], 0, v[146:147]
	ds_read_b128 v[146:149], v152
	global_load_dwordx4 v[150:153], v[150:151], off
	s_nop 0
	global_load_dwordx4 v[154:157], v[154:155], off
	v_add_u32_e32 v135, 0x100, v131
	s_addk_i32 s16, 0x400
	s_cmpk_eq_i32 s16, 0x1000
	v_mov_b64_e32 v[160:161], v[170:171]
	v_lshlrev_b32_e32 v162, 16, v160
	v_and_b32_e32 v163, 0xffff0000, v160
	s_waitcnt lgkmcnt(0)
	v_pk_fma_f32 v[146:147], v[162:163], s[2:3], v[146:147] op_sel_hi:[1,0,1]
	s_nop 0
	v_pk_add_f32 v[146:147], v[146:147], v[138:139] neg_lo:[0,1] neg_hi:[0,1]
	s_nop 0
	v_pk_mul_f32 v[146:147], v[136:137], v[146:147]
	s_waitcnt vmcnt(0)
	v_pk_fma_f32 v[146:147], v[150:151], v[146:147], v[154:155]
	v_lshlrev_b32_e32 v150, 16, v161
	v_and_b32_e32 v151, 0xffff0000, v161
	v_pk_fma_f32 v[148:149], v[150:151], s[2:3], v[148:149] op_sel_hi:[1,0,1]
	v_cvt_pk_bf16_f32 v146, v146, v147
	v_pk_add_f32 v[148:149], v[148:149], v[138:139] neg_lo:[0,1] neg_hi:[0,1]
	s_nop 0
	v_pk_mul_f32 v[148:149], v[136:137], v[148:149]
	s_nop 0
	v_pk_fma_f32 v[148:149], v[152:153], v[148:149], v[156:157]
	s_nop 0
	v_cvt_pk_bf16_f32 v147, v148, v149
	v_bfe_u32 v149, v135, 3, 7
	v_ashrrev_i32_e32 v135, 7, v135
	v_and_or_b32 v135, v135, -8, v141
	v_lshlrev_b32_e32 v148, 2, v135
	global_store_dwordx2 v[158:159], v[146:147], off
	v_lshlrev_b32_e32 v146, 4, v135
	v_add_u32_e32 v135, s38, v148
	v_ashrrev_i32_e32 v150, 5, v135
	v_ashrrev_i32_e32 v151, 31, v150
	v_mad_u32_u24 v152, v149, s94, v146
	v_or_b32_e32 v146, s39, v149
	v_mov_b32_e32 v147, v1
	v_lshlrev_b64 v[150:151], 21, v[150:151]
	v_lshl_add_u64 v[150:151], s[90:91], 0, v[150:151]
	v_lshlrev_b64 v[146:147], 6, v[146:147]
	v_lshl_add_u64 v[146:147], v[150:151], 0, v[146:147]
	v_lshl_add_u64 v[158:159], v[146:147], 0, v[0:1]
	v_lshl_or_b32 v135, v149, 3, v237
	v_ashrrev_i32_e32 v149, 31, v148
	v_lshlrev_b64 v[146:147], 2, v[148:149]
	v_lshl_add_u64 v[150:151], s[12:13], 0, v[146:147]
	v_lshl_add_u64 v[154:155], s[14:15], 0, v[146:147]
	ds_read_b64 v[162:163], v135
	ds_read_b128 v[146:149], v152
	global_load_dwordx4 v[150:153], v[150:151], off
	s_nop 0
	global_load_dwordx4 v[154:157], v[154:155], off
	v_add_u32_e32 v135, 0x200, v131
	v_add_u32_e32 v131, 0x300, v131
	v_mov_b64_e32 v[160:161], v[172:173]
	v_lshlrev_b32_e32 v164, 16, v160
	v_and_b32_e32 v165, 0xffff0000, v160
	s_waitcnt lgkmcnt(0)
	v_pk_fma_f32 v[146:147], v[164:165], s[2:3], v[146:147] op_sel_hi:[1,0,1]
	s_nop 0
	v_pk_add_f32 v[146:147], v[146:147], v[162:163] op_sel_hi:[1,0] neg_lo:[0,1] neg_hi:[0,1]
	s_nop 0
	v_pk_mul_f32 v[146:147], v[162:163], v[146:147] op_sel:[1,0]
	s_waitcnt vmcnt(0)
	v_pk_fma_f32 v[146:147], v[150:151], v[146:147], v[154:155]
	v_lshlrev_b32_e32 v150, 16, v161
	v_and_b32_e32 v151, 0xffff0000, v161
	v_pk_fma_f32 v[148:149], v[150:151], s[2:3], v[148:149] op_sel_hi:[1,0,1]
	v_cvt_pk_bf16_f32 v146, v146, v147
	v_pk_add_f32 v[148:149], v[148:149], v[162:163] op_sel_hi:[1,0] neg_lo:[0,1] neg_hi:[0,1]
	s_nop 0
	v_pk_mul_f32 v[148:149], v[162:163], v[148:149] op_sel:[1,0]
	s_nop 0
	v_pk_fma_f32 v[148:149], v[152:153], v[148:149], v[156:157]
	s_nop 0
	v_cvt_pk_bf16_f32 v147, v148, v149
	v_bfe_u32 v149, v135, 3, 7
	v_ashrrev_i32_e32 v135, 7, v135
	v_and_or_b32 v135, v135, -8, v141
	v_lshlrev_b32_e32 v148, 2, v135
	global_store_dwordx2 v[158:159], v[146:147], off
	v_lshlrev_b32_e32 v146, 4, v135
	v_add_u32_e32 v135, s38, v148
	v_ashrrev_i32_e32 v150, 5, v135
	v_ashrrev_i32_e32 v151, 31, v150
	v_mad_u32_u24 v152, v149, s94, v146
	v_or_b32_e32 v146, s39, v149
	v_mov_b32_e32 v147, v1
	v_lshlrev_b64 v[150:151], 21, v[150:151]
	v_lshl_add_u64 v[150:151], s[90:91], 0, v[150:151]
	v_lshlrev_b64 v[146:147], 6, v[146:147]
	v_lshl_add_u64 v[146:147], v[150:151], 0, v[146:147]
	v_lshl_add_u64 v[158:159], v[146:147], 0, v[0:1]
	v_lshl_or_b32 v135, v149, 3, v237
	v_ashrrev_i32_e32 v149, 31, v148
	v_lshlrev_b64 v[146:147], 2, v[148:149]
	v_lshl_add_u64 v[150:151], s[12:13], 0, v[146:147]
	v_lshl_add_u64 v[154:155], s[14:15], 0, v[146:147]
	ds_read_b64 v[162:163], v135
	ds_read_b128 v[146:149], v152
	global_load_dwordx4 v[150:153], v[150:151], off
	s_nop 0
	global_load_dwordx4 v[154:157], v[154:155], off
	v_bfe_u32 v135, v131, 3, 7
	v_ashrrev_i32_e32 v131, 7, v131
	v_and_or_b32 v131, v131, -8, v141
	v_mov_b64_e32 v[160:161], v[174:175]
	v_lshlrev_b32_e32 v164, 16, v160
	v_and_b32_e32 v165, 0xffff0000, v160
	s_waitcnt lgkmcnt(0)
	v_pk_fma_f32 v[146:147], v[164:165], s[2:3], v[146:147] op_sel_hi:[1,0,1]
	s_nop 0
	v_pk_add_f32 v[146:147], v[146:147], v[162:163] op_sel_hi:[1,0] neg_lo:[0,1] neg_hi:[0,1]
	s_nop 0
	v_pk_mul_f32 v[146:147], v[162:163], v[146:147] op_sel:[1,0]
	s_waitcnt vmcnt(0)
	v_pk_fma_f32 v[146:147], v[150:151], v[146:147], v[154:155]
	v_lshlrev_b32_e32 v150, 16, v161
	v_and_b32_e32 v151, 0xffff0000, v161
	v_pk_fma_f32 v[148:149], v[150:151], s[2:3], v[148:149] op_sel_hi:[1,0,1]
	v_cvt_pk_bf16_f32 v146, v146, v147
	v_pk_add_f32 v[148:149], v[148:149], v[162:163] op_sel_hi:[1,0] neg_lo:[0,1] neg_hi:[0,1]
	s_nop 0
	v_pk_mul_f32 v[148:149], v[162:163], v[148:149] op_sel:[1,0]
	s_nop 0
	v_pk_fma_f32 v[148:149], v[152:153], v[148:149], v[156:157]
	s_nop 0
	v_cvt_pk_bf16_f32 v147, v148, v149
	v_lshlrev_b32_e32 v148, 2, v131
	global_store_dwordx2 v[158:159], v[146:147], off
	v_lshlrev_b32_e32 v146, 4, v131
	v_add_u32_e32 v131, s38, v148
	v_ashrrev_i32_e32 v150, 5, v131
	v_ashrrev_i32_e32 v151, 31, v150
	v_mad_u32_u24 v152, v135, s94, v146
	v_or_b32_e32 v146, s39, v135
	v_mov_b32_e32 v147, v1
	v_lshlrev_b64 v[150:151], 21, v[150:151]
	v_lshl_add_u64 v[150:151], s[90:91], 0, v[150:151]
	v_lshlrev_b64 v[146:147], 6, v[146:147]
	v_lshl_add_u64 v[146:147], v[150:151], 0, v[146:147]
	v_lshl_add_u64 v[158:159], v[146:147], 0, v[0:1]
	v_ashrrev_i32_e32 v149, 31, v148
	v_lshlrev_b64 v[146:147], 2, v[148:149]
	v_lshl_or_b32 v131, v135, 3, v237
	v_lshl_add_u64 v[150:151], s[12:13], 0, v[146:147]
	v_lshl_add_u64 v[154:155], s[14:15], 0, v[146:147]
	ds_read_b64 v[162:163], v131
	ds_read_b128 v[146:149], v152
	global_load_dwordx4 v[150:153], v[150:151], off
	s_nop 0
	global_load_dwordx4 v[154:157], v[154:155], off
	v_mov_b64_e32 v[160:161], v[176:177]
	v_mov_b64_e32 v[170:171], v[178:179]
	v_mov_b64_e32 v[172:173], v[180:181]
	v_mov_b64_e32 v[174:175], v[182:183]
	v_mov_b64_e32 v[176:177], v[184:185]
	v_mov_b64_e32 v[178:179], v[186:187]
	v_mov_b64_e32 v[180:181], v[188:189]
	v_mov_b64_e32 v[182:183], v[190:191]
	v_mov_b64_e32 v[184:185], v[192:193]
	v_mov_b64_e32 v[186:187], v[194:195]
	v_mov_b64_e32 v[188:189], v[196:197]
	v_mov_b64_e32 v[190:191], v[198:199]
	v_mov_b64_e32 v[192:193], v[200:201]
	v_lshlrev_b32_e32 v164, 16, v160
	v_and_b32_e32 v165, 0xffff0000, v160
	s_waitcnt lgkmcnt(0)
	v_pk_fma_f32 v[146:147], v[164:165], s[2:3], v[146:147] op_sel_hi:[1,0,1]
	s_nop 0
	v_pk_add_f32 v[146:147], v[146:147], v[162:163] op_sel_hi:[1,0] neg_lo:[0,1] neg_hi:[0,1]
	s_nop 0
	v_pk_mul_f32 v[146:147], v[162:163], v[146:147] op_sel:[1,0]
	s_waitcnt vmcnt(0)
	v_pk_fma_f32 v[146:147], v[150:151], v[146:147], v[154:155]
	v_lshlrev_b32_e32 v150, 16, v161
	v_and_b32_e32 v151, 0xffff0000, v161
	v_pk_fma_f32 v[148:149], v[150:151], s[2:3], v[148:149] op_sel_hi:[1,0,1]
	v_cvt_pk_bf16_f32 v146, v146, v147
	v_pk_add_f32 v[148:149], v[148:149], v[162:163] op_sel_hi:[1,0] neg_lo:[0,1] neg_hi:[0,1]
	s_nop 0
	v_pk_mul_f32 v[148:149], v[162:163], v[148:149] op_sel:[1,0]
	s_nop 0
	v_pk_fma_f32 v[148:149], v[152:153], v[148:149], v[156:157]
	s_nop 0
	v_cvt_pk_bf16_f32 v147, v148, v149
	global_store_dwordx2 v[158:159], v[146:147], off
	s_cbranch_scc0 .LBB0_1358
	s_barrier
	s_and_saveexec_b64 s[16:17], s[50:51]
	s_cbranch_execz .LBB0_1361
	v_mul_u32_u24_e32 v131, 0x210, v144
	v_lshlrev_b32_e32 v132, 4, v140
	v_lshlrev_b32_e32 v133, 2, v143
	v_add3_u32 v131, v131, v132, v133
	ds_write_b128 v131, v[114:117]
	ds_write_b128 v131, v[118:121] offset:32
	ds_write_b128 v131, v[122:125] offset:64
	ds_write_b128 v131, v[126:129] offset:96
	ds_write_b128 v131, v[98:101] offset:128
	ds_write_b128 v131, v[102:105] offset:160
	ds_write_b128 v131, v[106:109] offset:192
	ds_write_b128 v131, v[110:113] offset:224
	ds_write_b128 v131, v[82:85] offset:16896
	ds_write_b128 v131, v[86:89] offset:16928
	ds_write_b128 v131, v[90:93] offset:16960
	ds_write_b128 v131, v[94:97] offset:16992
	ds_write_b128 v131, v[66:69] offset:17024
	ds_write_b128 v131, v[70:73] offset:17056
	ds_write_b128 v131, v[74:77] offset:17088
	ds_write_b128 v131, v[78:81] offset:17120
	ds_write_b128 v131, v[50:53] offset:33792
	ds_write_b128 v131, v[54:57] offset:33824
	ds_write_b128 v131, v[58:61] offset:33856
	ds_write_b128 v131, v[62:65] offset:33888
	ds_write_b128 v131, v[34:37] offset:33920
	ds_write_b128 v131, v[38:41] offset:33952
	ds_write_b128 v131, v[42:45] offset:33984
	ds_write_b128 v131, v[46:49] offset:34016
	ds_write_b128 v131, v[18:21] offset:50688
	ds_write_b128 v131, v[22:25] offset:50720
	ds_write_b128 v131, v[26:29] offset:50752
	ds_write_b128 v131, v[30:33] offset:50784
	ds_write_b128 v131, v[2:5] offset:50816
	ds_write_b128 v131, v[6:9] offset:50848
	ds_write_b128 v131, v[10:13] offset:50880
	ds_write_b128 v131, v[14:17] offset:50912

.LBB0_1362:
	v_add_u32_e32 v8, s16, v130
	v_ashrrev_i32_e32 v9, 7, v8
	v_and_or_b32 v9, v9, -8, v141
	v_lshlrev_b32_e32 v10, 2, v9
	v_lshl_add_u32 v16, v9, 4, v142
	v_add_u32_e32 v9, s38, v10
	v_ashrrev_i32_e32 v12, 5, v9
	v_ashrrev_i32_e32 v13, 31, v12
	v_lshlrev_b64 v[12:13], 21, v[12:13]
	v_lshl_add_u64 v[12:13], v[4:5], 0, v[12:13]
	v_lshl_add_u64 v[22:23], v[12:13], 0, v[0:1]
	s_and_b32 s32, s16, 0xfff
	s_cbranch_scc1 .Lrx_skip9
	global_load_dwordx2 v[170:171], v[22:23], off
	global_load_dwordx2 v[172:173], v[22:23], off offset:2048
	s_mov_b64 s[100:101], 0x1000
	v_lshl_add_u64 v[174:175], v[22:23], 0, s[100:101]
	global_load_dwordx2 v[176:177], v[174:175], off offset:2048
	global_load_dwordx2 v[174:175], v[174:175], off
	s_mov_b64 s[100:101], 0x200000
	v_lshl_add_u64 v[178:179], v[22:23], 0, s[100:101]
	s_mov_b64 s[100:101], 0x201000
	v_lshl_add_u64 v[182:183], v[22:23], 0, s[100:101]
	global_load_dwordx2 v[180:181], v[178:179], off offset:2048
	global_load_dwordx2 v[178:179], v[178:179], off
	global_load_dwordx2 v[184:185], v[182:183], off offset:2048
	global_load_dwordx2 v[182:183], v[182:183], off
	s_mov_b64 s[100:101], 0x400000
	v_lshl_add_u64 v[186:187], v[22:23], 0, s[100:101]
	s_mov_b64 s[100:101], 0x401000
	v_lshl_add_u64 v[190:191], v[22:23], 0, s[100:101]
	global_load_dwordx2 v[188:189], v[186:187], off offset:2048
	global_load_dwordx2 v[186:187], v[186:187], off
	global_load_dwordx2 v[192:193], v[190:191], off offset:2048
	global_load_dwordx2 v[190:191], v[190:191], off
	s_mov_b64 s[100:101], 0x600000
	v_lshl_add_u64 v[194:195], v[22:23], 0, s[100:101]
	s_mov_b64 s[100:101], 0x601000
	v_lshl_add_u64 v[198:199], v[22:23], 0, s[100:101]
	global_load_dwordx2 v[196:197], v[194:195], off offset:2048
	global_load_dwordx2 v[194:195], v[194:195], off
	global_load_dwordx2 v[200:201], v[198:199], off offset:2048
	global_load_dwordx2 v[198:199], v[198:199], off
	s_waitcnt vmcnt(0)
.Lrx_skip9:
	v_ashrrev_i32_e32 v11, 31, v10
	v_lshlrev_b64 v[10:11], 2, v[10:11]
	v_lshl_add_u64 v[14:15], s[12:13], 0, v[10:11]
	v_lshl_add_u64 v[18:19], s[14:15], 0, v[10:11]
	ds_read_b128 v[10:13], v16
	global_load_dwordx4 v[14:17], v[14:15], off
	s_nop 0
	global_load_dwordx4 v[18:21], v[18:19], off
	v_add_u32_e32 v9, 0x100, v8
	s_addk_i32 s16, 0x400
	s_cmpk_eq_i32 s16, 0x1000
	v_mov_b64_e32 v[24:25], v[170:171]
	v_lshlrev_b32_e32 v26, 16, v24
	v_and_b32_e32 v27, 0xffff0000, v24
	s_waitcnt lgkmcnt(0)
	v_pk_fma_f32 v[10:11], v[26:27], s[2:3], v[10:11] op_sel_hi:[1,0,1]
	s_nop 0
	v_pk_add_f32 v[10:11], v[10:11], v[6:7] neg_lo:[0,1] neg_hi:[0,1]
	s_nop 0
	v_pk_mul_f32 v[10:11], v[2:3], v[10:11]
	s_waitcnt vmcnt(0)
	v_pk_fma_f32 v[10:11], v[14:15], v[10:11], v[18:19]
	v_lshlrev_b32_e32 v14, 16, v25
	v_and_b32_e32 v15, 0xffff0000, v25
	v_pk_fma_f32 v[12:13], v[14:15], s[2:3], v[12:13] op_sel_hi:[1,0,1]
	v_cvt_pk_bf16_f32 v10, v10, v11
	v_pk_add_f32 v[12:13], v[12:13], v[6:7] neg_lo:[0,1] neg_hi:[0,1]
	s_nop 0
	v_pk_mul_f32 v[12:13], v[2:3], v[12:13]
	s_nop 0
	v_pk_fma_f32 v[12:13], v[16:17], v[12:13], v[20:21]
	s_nop 0
	v_cvt_pk_bf16_f32 v11, v12, v13
	v_bfe_u32 v13, v9, 3, 7
	v_ashrrev_i32_e32 v9, 7, v9
	v_and_or_b32 v9, v9, -8, v141
	v_lshlrev_b32_e32 v12, 2, v9
	global_store_dwordx2 v[22:23], v[10:11], off
	v_lshlrev_b32_e32 v10, 4, v9
	v_add_u32_e32 v9, s38, v12
	v_ashrrev_i32_e32 v14, 5, v9
	v_ashrrev_i32_e32 v15, 31, v14
	v_mad_u32_u24 v16, v13, s94, v10
	v_or_b32_e32 v10, s40, v13
	v_mov_b32_e32 v11, v1
	v_lshlrev_b64 v[14:15], 21, v[14:15]
	v_lshl_add_u64 v[14:15], s[90:91], 0, v[14:15]
	v_lshlrev_b64 v[10:11], 6, v[10:11]
	v_lshl_add_u64 v[10:11], v[14:15], 0, v[10:11]
	v_lshl_add_u64 v[22:23], v[10:11], 0, v[0:1]
	v_lshl_or_b32 v9, v13, 3, v238
	v_ashrrev_i32_e32 v13, 31, v12
	v_lshlrev_b64 v[10:11], 2, v[12:13]
	v_lshl_add_u64 v[14:15], s[12:13], 0, v[10:11]
	v_lshl_add_u64 v[18:19], s[14:15], 0, v[10:11]
	ds_read_b64 v[26:27], v9
	ds_read_b128 v[10:13], v16
	global_load_dwordx4 v[14:17], v[14:15], off
	s_nop 0
	global_load_dwordx4 v[18:21], v[18:19], off
	v_add_u32_e32 v9, 0x200, v8
	v_add_u32_e32 v8, 0x300, v8
	v_mov_b64_e32 v[24:25], v[172:173]
	v_lshlrev_b32_e32 v28, 16, v24
	v_and_b32_e32 v29, 0xffff0000, v24
	s_waitcnt lgkmcnt(0)
	v_pk_fma_f32 v[10:11], v[28:29], s[2:3], v[10:11] op_sel_hi:[1,0,1]
	s_nop 0
	v_pk_add_f32 v[10:11], v[10:11], v[26:27] op_sel_hi:[1,0] neg_lo:[0,1] neg_hi:[0,1]
	s_nop 0
	v_pk_mul_f32 v[10:11], v[26:27], v[10:11] op_sel:[1,0]
	s_waitcnt vmcnt(0)
	v_pk_fma_f32 v[10:11], v[14:15], v[10:11], v[18:19]
	v_lshlrev_b32_e32 v14, 16, v25
	v_and_b32_e32 v15, 0xffff0000, v25
	v_pk_fma_f32 v[12:13], v[14:15], s[2:3], v[12:13] op_sel_hi:[1,0,1]
	v_cvt_pk_bf16_f32 v10, v10, v11
	v_pk_add_f32 v[12:13], v[12:13], v[26:27] op_sel_hi:[1,0] neg_lo:[0,1] neg_hi:[0,1]
	s_nop 0
	v_pk_mul_f32 v[12:13], v[26:27], v[12:13] op_sel:[1,0]
	s_nop 0
	v_pk_fma_f32 v[12:13], v[16:17], v[12:13], v[20:21]
	s_nop 0
	v_cvt_pk_bf16_f32 v11, v12, v13
	v_bfe_u32 v13, v9, 3, 7
	v_ashrrev_i32_e32 v9, 7, v9
	v_and_or_b32 v9, v9, -8, v141
	v_lshlrev_b32_e32 v12, 2, v9
	global_store_dwordx2 v[22:23], v[10:11], off
	v_lshlrev_b32_e32 v10, 4, v9
	v_add_u32_e32 v9, s38, v12
	v_ashrrev_i32_e32 v14, 5, v9
	v_ashrrev_i32_e32 v15, 31, v14
	v_mad_u32_u24 v16, v13, s94, v10
	v_or_b32_e32 v10, s40, v13
	v_mov_b32_e32 v11, v1
	v_lshlrev_b64 v[14:15], 21, v[14:15]
	v_lshl_add_u64 v[14:15], s[90:91], 0, v[14:15]
	v_lshlrev_b64 v[10:11], 6, v[10:11]
	v_lshl_add_u64 v[10:11], v[14:15], 0, v[10:11]
	v_lshl_add_u64 v[22:23], v[10:11], 0, v[0:1]
	v_lshl_or_b32 v9, v13, 3, v238
	v_ashrrev_i32_e32 v13, 31, v12
	v_lshlrev_b64 v[10:11], 2, v[12:13]
	v_lshl_add_u64 v[14:15], s[12:13], 0, v[10:11]
	v_lshl_add_u64 v[18:19], s[14:15], 0, v[10:11]
	ds_read_b64 v[26:27], v9
	ds_read_b128 v[10:13], v16
	global_load_dwordx4 v[14:17], v[14:15], off
	s_nop 0
	global_load_dwordx4 v[18:21], v[18:19], off
	v_mov_b32_e32 v9, v1
	v_mov_b64_e32 v[24:25], v[174:175]
	v_lshlrev_b32_e32 v28, 16, v24
	v_and_b32_e32 v29, 0xffff0000, v24
	s_waitcnt lgkmcnt(0)
	v_pk_fma_f32 v[10:11], v[28:29], s[2:3], v[10:11] op_sel_hi:[1,0,1]
	s_nop 0
	v_pk_add_f32 v[10:11], v[10:11], v[26:27] op_sel_hi:[1,0] neg_lo:[0,1] neg_hi:[0,1]
	s_nop 0
	v_pk_mul_f32 v[10:11], v[26:27], v[10:11] op_sel:[1,0]
	s_waitcnt vmcnt(0)
	v_pk_fma_f32 v[10:11], v[14:15], v[10:11], v[18:19]
	v_lshlrev_b32_e32 v14, 16, v25
	v_and_b32_e32 v15, 0xffff0000, v25
	v_pk_fma_f32 v[12:13], v[14:15], s[2:3], v[12:13] op_sel_hi:[1,0,1]
	v_cvt_pk_bf16_f32 v10, v10, v11
	v_pk_add_f32 v[12:13], v[12:13], v[26:27] op_sel_hi:[1,0] neg_lo:[0,1] neg_hi:[0,1]
	s_nop 0
	v_pk_mul_f32 v[12:13], v[26:27], v[12:13] op_sel:[1,0]
	s_nop 0
	v_pk_fma_f32 v[12:13], v[16:17], v[12:13], v[20:21]
	s_nop 0
	v_cvt_pk_bf16_f32 v11, v12, v13
	global_store_dwordx2 v[22:23], v[10:11], off
	v_bfe_u32 v11, v8, 3, 7
	v_ashrrev_i32_e32 v8, 7, v8
	v_and_or_b32 v10, v8, -8, v141
	v_lshlrev_b32_e32 v8, 4, v10
	v_lshlrev_b32_e32 v10, 2, v10
	v_add_u32_e32 v12, s38, v10
	v_ashrrev_i32_e32 v12, 5, v12
	v_ashrrev_i32_e32 v13, 31, v12
	v_mad_u32_u24 v14, v11, s94, v8
	v_or_b32_e32 v8, s40, v11
	v_lshlrev_b64 v[12:13], 21, v[12:13]
	v_lshl_add_u64 v[12:13], s[90:91], 0, v[12:13]
	v_lshlrev_b64 v[8:9], 6, v[8:9]
	v_lshl_add_u64 v[8:9], v[12:13], 0, v[8:9]
	v_lshl_add_u64 v[20:21], v[8:9], 0, v[0:1]
	v_lshl_or_b32 v8, v11, 3, v238
	v_ashrrev_i32_e32 v11, 31, v10
	ds_read_b64 v[24:25], v8
	v_lshlrev_b64 v[8:9], 2, v[10:11]
	v_lshl_add_u64 v[12:13], s[12:13], 0, v[8:9]
	v_lshl_add_u64 v[16:17], s[14:15], 0, v[8:9]
	ds_read_b128 v[8:11], v14
	global_load_dwordx4 v[12:15], v[12:13], off
	s_nop 0
	global_load_dwordx4 v[16:19], v[16:17], off
	v_mov_b64_e32 v[22:23], v[176:177]
	v_mov_b64_e32 v[170:171], v[178:179]
	v_mov_b64_e32 v[172:173], v[180:181]
	v_mov_b64_e32 v[174:175], v[182:183]
	v_mov_b64_e32 v[176:177], v[184:185]
	v_mov_b64_e32 v[178:179], v[186:187]
	v_mov_b64_e32 v[180:181], v[188:189]
	v_mov_b64_e32 v[182:183], v[190:191]
	v_mov_b64_e32 v[184:185], v[192:193]
	v_mov_b64_e32 v[186:187], v[194:195]
	v_mov_b64_e32 v[188:189], v[196:197]
	v_mov_b64_e32 v[190:191], v[198:199]
	v_mov_b64_e32 v[192:193], v[200:201]
	v_lshlrev_b32_e32 v26, 16, v22
	v_and_b32_e32 v27, 0xffff0000, v22
	s_waitcnt lgkmcnt(0)
	v_pk_fma_f32 v[8:9], v[26:27], s[2:3], v[8:9] op_sel_hi:[1,0,1]
	s_nop 0
	v_pk_add_f32 v[8:9], v[8:9], v[24:25] op_sel_hi:[1,0] neg_lo:[0,1] neg_hi:[0,1]
	s_nop 0
	v_pk_mul_f32 v[8:9], v[24:25], v[8:9] op_sel:[1,0]
	s_waitcnt vmcnt(0)
	v_pk_fma_f32 v[8:9], v[12:13], v[8:9], v[16:17]
	v_lshlrev_b32_e32 v12, 16, v23
	v_and_b32_e32 v13, 0xffff0000, v23
	v_pk_fma_f32 v[10:11], v[12:13], s[2:3], v[10:11] op_sel_hi:[1,0,1]
	v_cvt_pk_bf16_f32 v8, v8, v9
	v_pk_add_f32 v[10:11], v[10:11], v[24:25] op_sel_hi:[1,0] neg_lo:[0,1] neg_hi:[0,1]
	s_nop 0
	v_pk_mul_f32 v[10:11], v[24:25], v[10:11] op_sel:[1,0]
	s_nop 0
	v_pk_fma_f32 v[10:11], v[14:15], v[10:11], v[18:19]
	s_nop 0
	v_cvt_pk_bf16_f32 v9, v10, v11
	global_store_dwordx2 v[20:21], v[8:9], off
	s_cbranch_scc0 .LBB0_1362
	v_readlane_b32 s12, v253, 22
	s_add_i32 s37, s37, s12
	v_readlane_b32 s12, v253, 17
	s_add_i32 s36, s36, s12
	v_readlane_b32 s12, v253, 23
	s_add_i32 s35, s35, s12
	s_cmp_gt_u32 s37, 63
	s_barrier
	s_cbranch_scc0 .LBB0_1321
	s_branch .LBB0_1318

; DI f32x16 mfma32(bf16x8 a, bf16x8 b, f32x16 c) { return __builtin_amdgcn_mfma_f32_32x32x16_bf16(a, b, c, 0, 0, 0); }
; DI f32x16 zero16() { f32x16 z; for (int i = 0; i < 16; ++i) z[i] = 0.f; return z; }
; DI void cross_item(const Params& P0_, int b, int item, uchar* smem) {
;     ...
;   for (int t = 0; t < 4; ++t) {
;     __syncthreads();
;     for (int i = 0; i < 8; ++i) {
;       int c = tid + 256 * i, row = c >> 5, kc = c & 31;
;       const u16* src = KV + ((size_t)b * 256 + t * 64 + row) * 2048 + hd * 256 + kc * 8;
;       *(uint4*)(Ks + row * 528 + kc * 16) = *(const uint4*)src;
;       *(uint4*)(Vs + row * 528 + kc * 16) = *(const uint4*)(src + 1024);
;     }
;     __syncthreads();
;     f32x16 st[2]; st[0] = zero16(); st[1] = zero16();
; #pragma unroll 4
;     for (int s = 0; s < 16; ++s) {
;       bf16x8 qf = *(const bf16x8*)(qrow + s * 512);
; #pragma unroll
;       for (int kt = 0; kt < 2; ++kt) {
;         bf16x8 kf = *(const bf16x8*)(Ks + (32 * kt + r31) * 528 + (2 * s + h) * 16);
;         st[kt] = mfma32(kf, qf, st[kt]);
;       }
;     }
.LBB0_1482:
	s_lshl_b32 s14, s11, 6
	s_mov_b32 s21, s45
	s_add_i32 s20, s16, s14
	s_barrier
	v_lshl_add_u64 v[240:241], s[20:21], 0, v[172:173]
	v_lshlrev_b64 v[240:241], 12, v[240:241]
	v_lshl_add_u64 v[240:241], v[170:171], 0, v[240:241]
	global_load_dwordx4 v[130:133], v[240:241], off
	global_load_dwordx4 v[134:137], v[240:241], off offset:2048
	v_lshl_add_u64 v[240:241], s[20:21], 0, v[176:177]
	v_lshlrev_b64 v[240:241], 12, v[240:241]
	v_lshl_add_u64 v[240:241], v[170:171], 0, v[240:241]
	global_load_dwordx4 v[138:141], v[240:241], off
	global_load_dwordx4 v[142:145], v[240:241], off offset:2048
	v_lshl_add_u64 v[240:241], s[20:21], 0, v[180:181]
	v_lshlrev_b64 v[240:241], 12, v[240:241]
	v_lshl_add_u64 v[240:241], v[170:171], 0, v[240:241]
	global_load_dwordx4 v[146:149], v[240:241], off
	global_load_dwordx4 v[150:153], v[240:241], off offset:2048
	v_lshl_add_u64 v[240:241], s[20:21], 0, v[184:185]
	v_lshlrev_b64 v[240:241], 12, v[240:241]
	v_lshl_add_u64 v[240:241], v[170:171], 0, v[240:241]
	global_load_dwordx4 v[154:157], v[240:241], off
	global_load_dwordx4 v[158:161], v[240:241], off offset:2048
	s_waitcnt vmcnt(7)
	ds_write_b128 v174, v[130:133]
	s_waitcnt vmcnt(6)
	ds_write_b128 v175, v[134:137]
	s_waitcnt vmcnt(5)
	ds_write_b128 v178, v[138:141]
	s_waitcnt vmcnt(4)
	ds_write_b128 v179, v[142:145]
	s_waitcnt vmcnt(3)
	ds_write_b128 v182, v[146:149]
	s_waitcnt vmcnt(2)
	ds_write_b128 v183, v[150:153]
	s_waitcnt vmcnt(1)
	ds_write_b128 v186, v[154:157]
	s_waitcnt vmcnt(0)
	ds_write_b128 v187, v[158:161]
	s_waitcnt lgkmcnt(0)
	v_lshl_add_u64 v[240:241], s[20:21], 0, v[188:189]
	v_lshlrev_b64 v[240:241], 12, v[240:241]
	v_lshl_add_u64 v[240:241], v[170:171], 0, v[240:241]
	global_load_dwordx4 v[130:133], v[240:241], off
	global_load_dwordx4 v[134:137], v[240:241], off offset:2048
	v_lshl_add_u64 v[240:241], s[20:21], 0, v[192:193]
	v_lshlrev_b64 v[240:241], 12, v[240:241]
	v_lshl_add_u64 v[240:241], v[170:171], 0, v[240:241]
	global_load_dwordx4 v[138:141], v[240:241], off
	global_load_dwordx4 v[142:145], v[240:241], off offset:2048
	v_lshl_add_u64 v[240:241], s[20:21], 0, v[196:197]
	v_lshlrev_b64 v[240:241], 12, v[240:241]
	v_lshl_add_u64 v[240:241], v[170:171], 0, v[240:241]
	global_load_dwordx4 v[146:149], v[240:241], off
	global_load_dwordx4 v[150:153], v[240:241], off offset:2048
	v_lshl_add_u64 v[240:241], s[20:21], 0, v[200:201]
	v_lshlrev_b64 v[240:241], 12, v[240:241]
	v_lshl_add_u64 v[240:241], v[170:171], 0, v[240:241]
	global_load_dwordx4 v[154:157], v[240:241], off
	global_load_dwordx4 v[158:161], v[240:241], off offset:2048
	s_waitcnt vmcnt(7)
	ds_write_b128 v190, v[130:133]
	s_waitcnt vmcnt(6)
	ds_write_b128 v191, v[134:137]
	s_waitcnt vmcnt(5)
	ds_write_b128 v194, v[138:141]
	s_waitcnt vmcnt(4)
	ds_write_b128 v195, v[142:145]
	s_waitcnt vmcnt(3)
	ds_write_b128 v198, v[146:149]
	s_waitcnt vmcnt(2)
	ds_write_b128 v199, v[150:153]
	s_waitcnt vmcnt(1)
	ds_write_b128 v202, v[154:157]
	s_waitcnt vmcnt(0)
	ds_write_b128 v203, v[158:161]
	v_mov_b64_e32 v[206:207], v[204:205]
	s_mov_b32 s14, 0
	global_load_dwordx4 v[224:227], v[206:207], off offset:-2048
	s_waitcnt lgkmcnt(0)
	v_mov_b32_e32 v146, 0
	v_mov_b32_e32 v147, v163
	v_mov_b32_e32 v148, v163
	v_mov_b32_e32 v149, v163
	v_mov_b32_e32 v150, v163
	v_mov_b32_e32 v151, v163
	v_mov_b32_e32 v152, v163
	v_mov_b32_e32 v153, v163
	v_mov_b32_e32 v154, v163
	v_mov_b32_e32 v155, v163
	v_mov_b32_e32 v156, v163
	v_mov_b32_e32 v157, v163
	v_mov_b32_e32 v158, v163
	v_mov_b32_e32 v159, v163
	v_mov_b32_e32 v160, v163
	v_mov_b32_e32 v161, v163
	v_mov_b32_e32 v130, 0
	v_mov_b32_e32 v131, v163
	v_mov_b32_e32 v132, v163
	v_mov_b32_e32 v133, v163
	v_mov_b32_e32 v134, v163
	v_mov_b32_e32 v135, v163
	v_mov_b32_e32 v136, v163
	v_mov_b32_e32 v137, v163
	v_mov_b32_e32 v138, v163
	v_mov_b32_e32 v139, v163
	v_mov_b32_e32 v140, v163
	v_mov_b32_e32 v141, v163
	v_mov_b32_e32 v142, v163
	v_mov_b32_e32 v143, v163
	v_mov_b32_e32 v144, v163
	v_mov_b32_e32 v145, v163
	s_barrier
.LBB0_1483:
	v_add_u32_e32 v0, s14, v214
	s_addk_i32 s14, 0x80
	global_load_dwordx4 v[244:247], v[206:207], off offset:-1024
	ds_read_b128 v[240:243], v0
	s_waitcnt vmcnt(1) lgkmcnt(0)
	v_mfma_f32_32x32x16_bf16 v[146:161], v[240:243], v[224:227], v[146:161]
	ds_read_b128 v[240:243], v0 offset:16896
	s_waitcnt lgkmcnt(0)
	v_mfma_f32_32x32x16_bf16 v[130:145], v[240:243], v[224:227], v[130:145]
	global_load_dwordx4 v[224:227], v[206:207], off offset:0
	ds_read_b128 v[240:243], v0 offset:32
	s_waitcnt vmcnt(1) lgkmcnt(0)
	v_mfma_f32_32x32x16_bf16 v[146:161], v[240:243], v[244:247], v[146:161]
	ds_read_b128 v[240:243], v0 offset:16928
	s_waitcnt lgkmcnt(0)
	v_mfma_f32_32x32x16_bf16 v[130:145], v[240:243], v[244:247], v[130:145]
	global_load_dwordx4 v[244:247], v[206:207], off offset:1024
	ds_read_b128 v[240:243], v0 offset:64
	s_waitcnt vmcnt(1) lgkmcnt(0)
	v_mfma_f32_32x32x16_bf16 v[146:161], v[240:243], v[224:227], v[146:161]
	ds_read_b128 v[240:243], v0 offset:16960
	s_waitcnt lgkmcnt(0)
	v_mfma_f32_32x32x16_bf16 v[130:145], v[240:243], v[224:227], v[130:145]
	s_cmpk_eq_i32 s14, 0x200
	s_cbranch_scc1 .Lxq_last
	global_load_dwordx4 v[224:227], v[206:207], off offset:2048
	ds_read_b128 v[240:243], v0 offset:96
	s_waitcnt vmcnt(1) lgkmcnt(0)
	s_branch .Lxq_go
.Lxq_last:
	ds_read_b128 v[240:243], v0 offset:96
	s_waitcnt vmcnt(0) lgkmcnt(0)
; DI f32x16 mfma32(bf16x8 a, bf16x8 b, f32x16 c) { return __builtin_amdgcn_mfma_f32_32x32x16_bf16(a, b, c, 0, 0, 0); }
; template <int NO, bool COND = true>
; DI void softmax_far(f32x16 st[2], float c2, float b2, float& m, float& lsum, f32x16* O, bf16x8 pf[4]) {
;   float mr = fmaxf(max16(st[0]), max16(st[1]));
;   float mx = fmaxf(m, mr * c2 + b2);
;   mx = fmaxf(mx, __shfl_xor(mx, 32, 64));
;   sm_rescale<NO, COND>(m, mx, lsum, O);
; DI void cross_item(const Params& P0_, int b, int item, uchar* smem) {
;     ...
;     for (int s = 0; s < 16; ++s) {
;       bf16x8 qf = *(const bf16x8*)(qrow + s * 512);
; #pragma unroll
;       for (int kt = 0; kt < 2; ++kt) {
;         bf16x8 kf = *(const bf16x8*)(Ks + (32 * kt + r31) * 528 + (2 * s + h) * 16);
;         st[kt] = mfma32(kf, qf, st[kt]);
;       }
;     }
;     bf16x8 pf[4];
;     softmax_far<8>(st, 0.0625f * LOG2E, 0.f, m, ls, O, pf);
.Lxq_go:
	v_mfma_f32_32x32x16_bf16 v[146:161], v[240:243], v[244:247], v[146:161]
	ds_read_b128 v[240:243], v0 offset:16992
	s_waitcnt lgkmcnt(0)
	v_mfma_f32_32x32x16_bf16 v[130:145], v[240:243], v[244:247], v[130:145]
	v_lshl_add_u64 v[206:207], v[206:207], 0, s[30:31]
	s_cmpk_eq_i32 s14, 0x200
	s_cbranch_scc0 .LBB0_1483
	s_nop 7
	v_max_f32_e32 v207, v153, v153
	v_max_f32_e32 v216, v152, v152
	v_max_f32_e32 v207, v216, v207
	v_max3_f32 v216, v155, v156, v157
	v_max_f32_e32 v217, v159, v159
	v_max_f32_e32 v224, v158, v158
	v_max3_f32 v0, v146, v147, v148
	v_max3_f32 v206, v149, v150, v151
	v_max_f32_e32 v217, v224, v217
	v_max3_f32 v207, v207, v154, v216
	v_max3_f32 v0, v0, v206, v207
	v_max3_f32 v206, v217, v160, v161
	v_max_f32_e32 v207, v131, v131
	v_max_f32_e32 v216, v130, v130
	v_max_f32_e32 v217, v137, v137
	v_max_f32_e32 v224, v136, v136
	v_max_f32_e32 v225, v143, v143
	v_max_f32_e32 v226, v142, v142
	v_max_f32_e32 v207, v216, v207
	v_max3_f32 v216, v133, v134, v135
	v_max_f32_e32 v217, v224, v217
	v_max3_f32 v224, v139, v140, v141
	v_max_f32_e32 v225, v226, v225
	v_max3_f32 v207, v207, v132, v216
	v_max3_f32 v216, v217, v138, v224
	v_max3_f32 v217, v225, v144, v145
	v_max3_f32 v207, v207, v216, v217
	v_max3_f32 v0, v0, v206, v207
	s_mov_b32 s14, 0x3db8aa3b
	v_fma_f32 v0, v0, s14, 0
	v_max_f32_e32 v206, v215, v215
	v_max_f32_e32 v0, v206, v0
	ds_bpermute_b32 v206, v212, v0
	s_waitcnt lgkmcnt(0)
	v_max_f32_e32 v206, v206, v206
	v_max_f32_e32 v206, v0, v206
	v_cmp_gt_f32_e32 vcc, v206, v215
	s_cbranch_vccz .LBB0_1486
	v_sub_f32_e32 v0, v215, v206
	v_exp_f32_e32 v0, v0
	s_nop 0
	v_mul_f32_e32 v165, v165, v0
	v_pk_mul_f32 v[128:129], v[128:129], v[0:1] op_sel_hi:[1,0]
	v_pk_mul_f32 v[126:127], v[126:127], v[0:1] op_sel_hi:[1,0]
	v_pk_mul_f32 v[124:125], v[124:125], v[0:1] op_sel_hi:[1,0]
	v_pk_mul_f32 v[122:123], v[122:123], v[0:1] op_sel_hi:[1,0]
	v_pk_mul_f32 v[120:121], v[120:121], v[0:1] op_sel_hi:[1,0]
	v_pk_mul_f32 v[118:119], v[118:119], v[0:1] op_sel_hi:[1,0]
	v_pk_mul_f32 v[116:117], v[116:117], v[0:1] op_sel_hi:[1,0]
	v_pk_mul_f32 v[114:115], v[114:115], v[0:1] op_sel_hi:[1,0]
	v_pk_mul_f32 v[112:113], v[112:113], v[0:1] op_sel_hi:[1,0]
	v_pk_mul_f32 v[110:111], v[110:111], v[0:1] op_sel_hi:[1,0]
	v_pk_mul_f32 v[108:109], v[108:109], v[0:1] op_sel_hi:[1,0]
	v_pk_mul_f32 v[106:107], v[106:107], v[0:1] op_sel_hi:[1,0]
	v_pk_mul_f32 v[104:105], v[104:105], v[0:1] op_sel_hi:[1,0]
	v_pk_mul_f32 v[102:103], v[102:103], v[0:1] op_sel_hi:[1,0]
	v_pk_mul_f32 v[100:101], v[100:101], v[0:1] op_sel_hi:[1,0]
	v_pk_mul_f32 v[98:99], v[98:99], v[0:1] op_sel_hi:[1,0]
	v_pk_mul_f32 v[96:97], v[96:97], v[0:1] op_sel_hi:[1,0]
	v_pk_mul_f32 v[94:95], v[94:95], v[0:1] op_sel_hi:[1,0]
	v_pk_mul_f32 v[92:93], v[92:93], v[0:1] op_sel_hi:[1,0]
	v_pk_mul_f32 v[90:91], v[90:91], v[0:1] op_sel_hi:[1,0]
	v_pk_mul_f32 v[88:89], v[88:89], v[0:1] op_sel_hi:[1,0]
	v_pk_mul_f32 v[86:87], v[86:87], v[0:1] op_sel_hi:[1,0]
	v_pk_mul_f32 v[84:85], v[84:85], v[0:1] op_sel_hi:[1,0]
	v_pk_mul_f32 v[82:83], v[82:83], v[0:1] op_sel_hi:[1,0]
	v_pk_mul_f32 v[80:81], v[80:81], v[0:1] op_sel_hi:[1,0]
	v_pk_mul_f32 v[78:79], v[78:79], v[0:1] op_sel_hi:[1,0]
	v_pk_mul_f32 v[76:77], v[76:77], v[0:1] op_sel_hi:[1,0]
	v_pk_mul_f32 v[74:75], v[74:75], v[0:1] op_sel_hi:[1,0]
	v_pk_mul_f32 v[72:73], v[72:73], v[0:1] op_sel_hi:[1,0]
	v_pk_mul_f32 v[70:71], v[70:71], v[0:1] op_sel_hi:[1,0]
	v_pk_mul_f32 v[68:69], v[68:69], v[0:1] op_sel_hi:[1,0]
	v_pk_mul_f32 v[66:67], v[66:67], v[0:1] op_sel_hi:[1,0]
	v_pk_mul_f32 v[64:65], v[64:65], v[0:1] op_sel_hi:[1,0]
	v_pk_mul_f32 v[62:63], v[62:63], v[0:1] op_sel_hi:[1,0]
	v_pk_mul_f32 v[60:61], v[60:61], v[0:1] op_sel_hi:[1,0]
	v_pk_mul_f32 v[58:59], v[58:59], v[0:1] op_sel_hi:[1,0]
	v_pk_mul_f32 v[56:57], v[56:57], v[0:1] op_sel_hi:[1,0]
	v_pk_mul_f32 v[54:55], v[54:55], v[0:1] op_sel_hi:[1,0]
	v_pk_mul_f32 v[52:53], v[52:53], v[0:1] op_sel_hi:[1,0]
	v_pk_mul_f32 v[50:51], v[50:51], v[0:1] op_sel_hi:[1,0]
	v_pk_mul_f32 v[48:49], v[48:49], v[0:1] op_sel_hi:[1,0]
	v_pk_mul_f32 v[46:47], v[46:47], v[0:1] op_sel_hi:[1,0]
	v_pk_mul_f32 v[44:45], v[44:45], v[0:1] op_sel_hi:[1,0]
	v_pk_mul_f32 v[42:43], v[42:43], v[0:1] op_sel_hi:[1,0]
	v_pk_mul_f32 v[40:41], v[40:41], v[0:1] op_sel_hi:[1,0]
	v_pk_mul_f32 v[38:39], v[38:39], v[0:1] op_sel_hi:[1,0]
	v_pk_mul_f32 v[36:37], v[36:37], v[0:1] op_sel_hi:[1,0]
	v_pk_mul_f32 v[34:35], v[34:35], v[0:1] op_sel_hi:[1,0]
	v_pk_mul_f32 v[32:33], v[32:33], v[0:1] op_sel_hi:[1,0]
	v_pk_mul_f32 v[30:31], v[30:31], v[0:1] op_sel_hi:[1,0]
	v_pk_mul_f32 v[28:29], v[28:29], v[0:1] op_sel_hi:[1,0]
	v_pk_mul_f32 v[26:27], v[26:27], v[0:1] op_sel_hi:[1,0]
	v_pk_mul_f32 v[24:25], v[24:25], v[0:1] op_sel_hi:[1,0]
	v_pk_mul_f32 v[22:23], v[22:23], v[0:1] op_sel_hi:[1,0]
	v_pk_mul_f32 v[20:21], v[20:21], v[0:1] op_sel_hi:[1,0]
	v_pk_mul_f32 v[18:19], v[18:19], v[0:1] op_sel_hi:[1,0]
	v_pk_mul_f32 v[16:17], v[16:17], v[0:1] op_sel_hi:[1,0]
	v_pk_mul_f32 v[14:15], v[14:15], v[0:1] op_sel_hi:[1,0]
	v_pk_mul_f32 v[12:13], v[12:13], v[0:1] op_sel_hi:[1,0]
	v_pk_mul_f32 v[10:11], v[10:11], v[0:1] op_sel_hi:[1,0]
	v_pk_mul_f32 v[8:9], v[8:9], v[0:1] op_sel_hi:[1,0]
	v_pk_mul_f32 v[6:7], v[6:7], v[0:1] op_sel_hi:[1,0]
	v_pk_mul_f32 v[4:5], v[4:5], v[0:1] op_sel_hi:[1,0]
	v_pk_mul_f32 v[2:3], v[2:3], v[0:1] op_sel_hi:[1,0]

.LBB0_1722:
	v_add_u32_e32 v131, s0, v134
	v_ashrrev_i32_e32 v0, 7, v131
	v_and_or_b32 v0, v0, -8, v151
	v_lshl_add_u32 v135, v0, 4, v152
	v_lshl_add_u32 v0, v0, 2, s39
	v_ashrrev_i32_e32 v138, 5, v0
	v_ashrrev_i32_e32 v139, 31, v138
	v_lshlrev_b64 v[138:139], 21, v[138:139]
	v_lshl_add_u64 v[138:139], v[132:133], 0, v[138:139]
	v_lshlrev_b32_e32 v0, 3, v151
	v_lshl_add_u64 v[138:139], v[138:139], 0, v[0:1]
	s_and_b32 s32, s0, 0x7ff
	s_cbranch_scc1 .Lrx_skip4
	global_load_dwordx2 v[186:187], v[138:139], off
	global_load_dwordx2 v[188:189], v[138:139], off offset:2048
	s_mov_b64 s[100:101], 0x1000
	v_lshl_add_u64 v[190:191], v[138:139], 0, s[100:101]
	global_load_dwordx2 v[192:193], v[190:191], off offset:2048
	global_load_dwordx2 v[190:191], v[190:191], off
	s_mov_b64 s[100:101], 0x200000
	v_lshl_add_u64 v[194:195], v[138:139], 0, s[100:101]
	s_mov_b64 s[100:101], 0x201000
	v_lshl_add_u64 v[198:199], v[138:139], 0, s[100:101]
	global_load_dwordx2 v[196:197], v[194:195], off offset:2048
	global_load_dwordx2 v[194:195], v[194:195], off
	global_load_dwordx2 v[200:201], v[198:199], off offset:2048
	global_load_dwordx2 v[198:199], v[198:199], off
	s_waitcnt vmcnt(0)
.Lrx_skip4:
	s_addk_i32 s0, 0x400
	s_cmpk_eq_i32 s0, 0x1000
	v_mov_b64_e32 v[138:139], v[186:187]
	v_lshlrev_b32_e32 v142, 16, v138
	v_and_b32_e32 v143, 0xffff0000, v138
	v_lshlrev_b32_e32 v144, 16, v139
	v_and_b32_e32 v145, 0xffff0000, v139
	ds_read_b128 v[138:141], v135
	s_waitcnt lgkmcnt(0)
	v_pk_fma_f32 v[138:139], v[142:143], s[2:3], v[138:139] op_sel_hi:[1,0,1]
	v_pk_fma_f32 v[140:141], v[144:145], s[2:3], v[140:141] op_sel_hi:[1,0,1]
	ds_write_b128 v135, v[138:141]
	v_add_u32_e32 v135, 0x100, v131
	v_bfe_u32 v136, v135, 3, 7
	v_ashrrev_i32_e32 v135, 7, v135
	v_and_or_b32 v135, v135, -8, v151
	v_lshlrev_b32_e32 v138, 4, v135
	v_lshl_add_u32 v135, v135, 2, s39
	v_mad_u32_u24 v146, v136, s94, v138
	v_ashrrev_i32_e32 v138, 5, v135
	v_ashrrev_i32_e32 v139, 31, v138
	v_or_b32_e32 v136, s40, v136
	v_lshlrev_b64 v[138:139], 21, v[138:139]
	v_lshl_add_u64 v[138:139], s[90:91], 0, v[138:139]
	v_lshlrev_b32_e32 v140, 6, v136
	v_mov_b32_e32 v141, v1
	v_lshl_add_u64 v[138:139], v[138:139], 0, v[140:141]
	v_lshl_add_u64 v[138:139], v[138:139], 0, v[0:1]
	v_add_u32_e32 v135, 0x200, v131
	v_bfe_u32 v136, v135, 3, 7
	v_ashrrev_i32_e32 v135, 7, v135
	v_and_or_b32 v135, v135, -8, v151
	v_add_u32_e32 v131, 0x300, v131
	v_mov_b64_e32 v[138:139], v[188:189]
	v_lshlrev_b32_e32 v142, 16, v138
	v_and_b32_e32 v143, 0xffff0000, v138
	v_lshlrev_b32_e32 v144, 16, v139
	v_and_b32_e32 v145, 0xffff0000, v139
	ds_read_b128 v[138:141], v146
	s_waitcnt lgkmcnt(0)
	v_pk_fma_f32 v[138:139], v[142:143], s[2:3], v[138:139] op_sel_hi:[1,0,1]
	v_pk_fma_f32 v[140:141], v[144:145], s[2:3], v[140:141] op_sel_hi:[1,0,1]
	ds_write_b128 v146, v[138:141]
	v_lshlrev_b32_e32 v138, 4, v135
	v_lshl_add_u32 v135, v135, 2, s39
	v_mad_u32_u24 v146, v136, s94, v138
	v_ashrrev_i32_e32 v138, 5, v135
	v_ashrrev_i32_e32 v139, 31, v138
	v_or_b32_e32 v136, s40, v136
	v_lshlrev_b64 v[138:139], 21, v[138:139]
	v_lshl_add_u64 v[138:139], s[90:91], 0, v[138:139]
	v_lshlrev_b32_e32 v140, 6, v136
	v_mov_b32_e32 v141, v1
	v_lshl_add_u64 v[138:139], v[138:139], 0, v[140:141]
	v_lshl_add_u64 v[138:139], v[138:139], 0, v[0:1]
	v_bfe_u32 v135, v131, 3, 7
	v_ashrrev_i32_e32 v131, 7, v131
	v_and_or_b32 v131, v131, -8, v151
	v_lshlrev_b32_e32 v136, 4, v131
	v_lshl_add_u32 v131, v131, 2, s39
	v_mad_u32_u24 v136, v135, s94, v136
	v_or_b32_e32 v135, s40, v135
	v_mov_b64_e32 v[138:139], v[190:191]
	v_lshlrev_b32_e32 v142, 16, v138
	v_and_b32_e32 v143, 0xffff0000, v138
	v_lshlrev_b32_e32 v144, 16, v139
	v_and_b32_e32 v145, 0xffff0000, v139
	ds_read_b128 v[138:141], v146
	s_waitcnt lgkmcnt(0)
	v_pk_fma_f32 v[138:139], v[142:143], s[2:3], v[138:139] op_sel_hi:[1,0,1]
	v_pk_fma_f32 v[140:141], v[144:145], s[2:3], v[140:141] op_sel_hi:[1,0,1]
	ds_write_b128 v146, v[138:141]
	v_ashrrev_i32_e32 v138, 5, v131
	v_ashrrev_i32_e32 v139, 31, v138
	v_lshlrev_b64 v[138:139], 21, v[138:139]
	v_lshl_add_u64 v[138:139], s[90:91], 0, v[138:139]
	v_lshlrev_b32_e32 v140, 6, v135
	v_mov_b32_e32 v141, v1
	v_lshl_add_u64 v[138:139], v[138:139], 0, v[140:141]
	v_lshl_add_u64 v[138:139], v[138:139], 0, v[0:1]
	v_mov_b64_e32 v[138:139], v[192:193]
	v_mov_b64_e32 v[186:187], v[194:195]
	v_mov_b64_e32 v[188:189], v[196:197]
	v_mov_b64_e32 v[190:191], v[198:199]
	v_mov_b64_e32 v[192:193], v[200:201]
	v_lshlrev_b32_e32 v142, 16, v138
	v_and_b32_e32 v143, 0xffff0000, v138
	v_lshlrev_b32_e32 v144, 16, v139
	v_and_b32_e32 v145, 0xffff0000, v139
	ds_read_b128 v[138:141], v136
	s_waitcnt lgkmcnt(0)
	v_pk_fma_f32 v[138:139], v[142:143], s[2:3], v[138:139] op_sel_hi:[1,0,1]
	v_pk_fma_f32 v[140:141], v[144:145], s[2:3], v[140:141] op_sel_hi:[1,0,1]
	ds_write_b128 v136, v[138:141]
	s_cbranch_scc0 .LBB0_1722
	s_lshl_b32 s1, s38, 8
	s_lshl_b32 s0, s40, 3
	s_and_b32 s1, s1, 0x700
	s_mov_b32 s17, s45
	s_or_b32 s16, s0, s1
	s_lshl_b64 s[16:17], s[16:17], 3
	s_add_u32 s16, s6, s16
	s_movk_i32 s1, 0x80
	s_addc_u32 s17, s7, s17
	v_cmp_gt_i32_e32 vcc, s1, v134
	v_mul_lo_u32 v131, v134, s94
	s_waitcnt lgkmcnt(0)
	s_barrier
	s_and_saveexec_b64 s[18:19], vcc
	s_cbranch_execz .LBB0_1727
	v_mov_b32_e32 v132, 0
	s_mov_b32 s1, 0
	v_mov_b32_e32 v133, v132

.LBB0_1730:
	v_add_u32_e32 v135, s1, v134
	v_ashrrev_i32_e32 v138, 7, v135
	v_and_or_b32 v138, v138, -8, v151
	v_lshl_add_u32 v146, v138, 4, v152
	v_lshl_add_u32 v138, v138, 2, s39
	v_ashrrev_i32_e32 v138, 5, v138
	v_ashrrev_i32_e32 v139, 31, v138
	v_lshlrev_b64 v[138:139], 21, v[138:139]
	v_lshl_add_u64 v[138:139], v[132:133], 0, v[138:139]
	v_lshl_add_u64 v[138:139], v[138:139], 0, v[0:1]
	s_and_b32 s32, s1, 0x7ff
	s_cbranch_scc1 .Lrx_skip3
	global_load_dwordx2 v[186:187], v[138:139], off
	global_load_dwordx2 v[188:189], v[138:139], off offset:2048
	s_mov_b64 s[100:101], 0x1000
	v_lshl_add_u64 v[190:191], v[138:139], 0, s[100:101]
	global_load_dwordx2 v[192:193], v[190:191], off offset:2048
	global_load_dwordx2 v[190:191], v[190:191], off
	s_mov_b64 s[100:101], 0x200000
	v_lshl_add_u64 v[194:195], v[138:139], 0, s[100:101]
	s_mov_b64 s[100:101], 0x201000
	v_lshl_add_u64 v[198:199], v[138:139], 0, s[100:101]
	global_load_dwordx2 v[196:197], v[194:195], off offset:2048
	global_load_dwordx2 v[194:195], v[194:195], off
	global_load_dwordx2 v[200:201], v[198:199], off offset:2048
	global_load_dwordx2 v[198:199], v[198:199], off
	s_waitcnt vmcnt(0)
.Lrx_skip3:
	s_addk_i32 s1, 0x400
	s_cmpk_lg_i32 s1, 0x1000
	v_mov_b64_e32 v[138:139], v[186:187]
	v_lshlrev_b32_e32 v142, 16, v138
	v_and_b32_e32 v143, 0xffff0000, v138
	v_lshlrev_b32_e32 v144, 16, v139
	v_and_b32_e32 v145, 0xffff0000, v139
	ds_read_b128 v[138:141], v146
	s_waitcnt lgkmcnt(0)
	v_pk_fma_f32 v[138:139], v[142:143], s[2:3], v[138:139] op_sel_hi:[1,0,1]
	v_pk_fma_f32 v[140:141], v[144:145], s[2:3], v[140:141] op_sel_hi:[1,0,1]
	ds_write_b128 v146, v[138:141]
	v_add_u32_e32 v138, 0x100, v135
	v_bfe_u32 v139, v138, 3, 7
	v_ashrrev_i32_e32 v138, 7, v138
	v_and_or_b32 v138, v138, -8, v151
	v_lshlrev_b32_e32 v140, 4, v138
	v_lshl_add_u32 v138, v138, 2, s39
	v_ashrrev_i32_e32 v138, 5, v138
	v_mad_u32_u24 v146, v139, s94, v140
	v_or_b32_e32 v140, s41, v139
	v_ashrrev_i32_e32 v139, 31, v138
	v_lshlrev_b64 v[138:139], 21, v[138:139]
	v_lshl_add_u64 v[138:139], s[90:91], 0, v[138:139]
	v_lshlrev_b32_e32 v140, 6, v140
	v_mov_b32_e32 v141, v1
	v_lshl_add_u64 v[138:139], v[138:139], 0, v[140:141]
	v_lshl_add_u64 v[138:139], v[138:139], 0, v[0:1]
	v_mov_b64_e32 v[138:139], v[188:189]
	v_lshlrev_b32_e32 v142, 16, v138
	v_and_b32_e32 v143, 0xffff0000, v138
	v_lshlrev_b32_e32 v144, 16, v139
	v_and_b32_e32 v145, 0xffff0000, v139
	ds_read_b128 v[138:141], v146
	s_waitcnt lgkmcnt(0)
	v_pk_fma_f32 v[138:139], v[142:143], s[2:3], v[138:139] op_sel_hi:[1,0,1]
	v_pk_fma_f32 v[140:141], v[144:145], s[2:3], v[140:141] op_sel_hi:[1,0,1]
	ds_write_b128 v146, v[138:141]
	v_add_u32_e32 v138, 0x200, v135
	v_bfe_u32 v139, v138, 3, 7
	v_ashrrev_i32_e32 v138, 7, v138
	v_and_or_b32 v138, v138, -8, v151
	v_lshlrev_b32_e32 v140, 4, v138
	v_lshl_add_u32 v138, v138, 2, s39
	v_ashrrev_i32_e32 v138, 5, v138
	v_mad_u32_u24 v146, v139, s94, v140
	v_or_b32_e32 v140, s41, v139
	v_ashrrev_i32_e32 v139, 31, v138
	v_lshlrev_b64 v[138:139], 21, v[138:139]
	v_lshl_add_u64 v[138:139], s[90:91], 0, v[138:139]
	v_lshlrev_b32_e32 v140, 6, v140
	v_mov_b32_e32 v141, v1
	v_lshl_add_u64 v[138:139], v[138:139], 0, v[140:141]
	v_lshl_add_u64 v[138:139], v[138:139], 0, v[0:1]
	v_add_u32_e32 v135, 0x300, v135
	v_mov_b64_e32 v[138:139], v[190:191]
	v_lshlrev_b32_e32 v142, 16, v138
	v_and_b32_e32 v143, 0xffff0000, v138
	v_lshlrev_b32_e32 v144, 16, v139
	v_and_b32_e32 v145, 0xffff0000, v139
	ds_read_b128 v[138:141], v146
	s_waitcnt lgkmcnt(0)
	v_pk_fma_f32 v[138:139], v[142:143], s[2:3], v[138:139] op_sel_hi:[1,0,1]
	v_pk_fma_f32 v[140:141], v[144:145], s[2:3], v[140:141] op_sel_hi:[1,0,1]
	ds_write_b128 v146, v[138:141]
	v_bfe_u32 v138, v135, 3, 7
	v_ashrrev_i32_e32 v135, 7, v135
	v_and_or_b32 v135, v135, -8, v151
	v_lshlrev_b32_e32 v139, 4, v135
	v_lshl_add_u32 v135, v135, 2, s39
	v_mad_u32_u24 v146, v138, s94, v139
	v_or_b32_e32 v140, s41, v138
	v_ashrrev_i32_e32 v138, 5, v135
	v_ashrrev_i32_e32 v139, 31, v138
	v_lshlrev_b64 v[138:139], 21, v[138:139]
	v_lshl_add_u64 v[138:139], s[90:91], 0, v[138:139]
	v_lshlrev_b32_e32 v140, 6, v140
	v_mov_b32_e32 v141, v1
	v_lshl_add_u64 v[138:139], v[138:139], 0, v[140:141]
	v_lshl_add_u64 v[138:139], v[138:139], 0, v[0:1]
	v_mov_b64_e32 v[138:139], v[192:193]
	v_mov_b64_e32 v[186:187], v[194:195]
	v_mov_b64_e32 v[188:189], v[196:197]
	v_mov_b64_e32 v[190:191], v[198:199]
	v_mov_b64_e32 v[192:193], v[200:201]
	v_lshlrev_b32_e32 v142, 16, v138
	v_and_b32_e32 v143, 0xffff0000, v138
	v_lshlrev_b32_e32 v144, 16, v139
	v_and_b32_e32 v145, 0xffff0000, v139
	ds_read_b128 v[138:141], v146
	s_waitcnt lgkmcnt(0)
	v_pk_fma_f32 v[138:139], v[142:143], s[2:3], v[138:139] op_sel_hi:[1,0,1]
	v_pk_fma_f32 v[140:141], v[144:145], s[2:3], v[140:141] op_sel_hi:[1,0,1]
	ds_write_b128 v146, v[138:141]
	s_cbranch_scc1 .LBB0_1730
	s_waitcnt lgkmcnt(0)
	s_barrier
	s_and_saveexec_b64 s[18:19], vcc
	s_cbranch_execz .LBB0_1735
	v_mov_b32_e32 v132, 0
	s_mov_b32 s1, 0
	v_mov_b32_e32 v133, v132

.LBB0_1755:
	v_add_u32_e32 v135, s22, v134
	v_ashrrev_i32_e32 v130, 7, v135
	v_and_or_b32 v155, v130, -8, v151
	v_lshlrev_b32_e32 v146, 2, v155
	v_add_u32_e32 v130, s39, v146
	v_ashrrev_i32_e32 v130, 5, v130
	v_ashrrev_i32_e32 v131, 31, v130
	v_lshlrev_b64 v[130:131], 21, v[130:131]
	v_lshl_add_u64 v[130:131], v[140:141], 0, v[130:131]
	v_lshl_add_u64 v[148:149], v[130:131], 0, v[0:1]
	s_and_b32 s32, s22, 0x7ff
	s_cbranch_scc1 .Lrx_skip2
	global_load_dwordx2 v[186:187], v[148:149], off
	global_load_dwordx2 v[188:189], v[148:149], off offset:2048
	s_mov_b64 s[100:101], 0x1000
	v_lshl_add_u64 v[190:191], v[148:149], 0, s[100:101]
	global_load_dwordx2 v[192:193], v[190:191], off offset:2048
	global_load_dwordx2 v[190:191], v[190:191], off
	s_mov_b64 s[100:101], 0x200000
	v_lshl_add_u64 v[194:195], v[148:149], 0, s[100:101]
	s_mov_b64 s[100:101], 0x201000
	v_lshl_add_u64 v[198:199], v[148:149], 0, s[100:101]
	global_load_dwordx2 v[196:197], v[194:195], off offset:2048
	global_load_dwordx2 v[194:195], v[194:195], off
	global_load_dwordx2 v[200:201], v[198:199], off offset:2048
	global_load_dwordx2 v[198:199], v[198:199], off
	s_waitcnt vmcnt(0)
.Lrx_skip2:
	v_ashrrev_i32_e32 v147, 31, v146
	v_lshlrev_b64 v[130:131], 2, v[146:147]
	v_lshl_add_u64 v[132:133], s[16:17], 0, v[130:131]
	v_lshl_add_u64 v[156:157], s[18:19], 0, v[130:131]
	global_load_dwordx4 v[130:133], v[132:133], off
	s_nop 0
	global_load_dwordx4 v[156:159], v[156:157], off
	v_cndmask_b32_e64 v160, 0, 1, s[10:11]
	v_lshl_add_u32 v155, v155, 4, v152
	v_cmp_ne_u32_e64 s[0:1], 1, v160
	ds_read_b128 v[160:163], v155
	s_andn2_b64 vcc, exec, s[10:11]
	v_mov_b64_e32 v[164:165], v[186:187]
	v_lshlrev_b32_e32 v170, 16, v164
	v_and_b32_e32 v171, 0xffff0000, v164
	v_lshlrev_b32_e32 v164, 16, v165
	v_and_b32_e32 v165, 0xffff0000, v165
	s_waitcnt lgkmcnt(0)
	v_pk_fma_f32 v[160:161], v[170:171], s[2:3], v[160:161] op_sel_hi:[1,0,1]
	v_pk_fma_f32 v[162:163], v[164:165], s[2:3], v[162:163] op_sel_hi:[1,0,1]
	v_pk_add_f32 v[160:161], v[160:161], v[142:143] neg_lo:[0,1] neg_hi:[0,1]
	v_pk_add_f32 v[162:163], v[162:163], v[142:143] neg_lo:[0,1] neg_hi:[0,1]
	v_pk_mul_f32 v[160:161], v[138:139], v[160:161]
	v_pk_mul_f32 v[162:163], v[138:139], v[162:163]
	s_waitcnt vmcnt(0)
	v_pk_fma_f32 v[130:131], v[130:131], v[160:161], v[156:157]
	v_pk_fma_f32 v[132:133], v[132:133], v[162:163], v[158:159]
	v_cvt_pk_bf16_f32 v156, v130, v131
	v_cvt_pk_bf16_f32 v157, v132, v133
	global_store_dwordx2 v[148:149], v[156:157], off
	s_cbranch_vccnz .LBB0_1757
	v_lshl_add_u64 v[146:147], v[146:147], 2, v[144:145]
	global_store_dwordx4 v[146:147], v[130:133], off
.LBB0_1757:
	s_nop 1
	v_add_u32_e32 v130, 0x100, v135
	v_bfe_u32 v155, v130, 3, 7
	v_ashrrev_i32_e32 v130, 7, v130
	v_and_or_b32 v160, v130, -8, v151
	v_lshlrev_b32_e32 v148, 2, v160
	v_add_u32_e32 v130, s39, v148
	v_ashrrev_i32_e32 v130, 5, v130
	v_ashrrev_i32_e32 v131, 31, v130
	v_or_b32_e32 v146, s40, v155
	v_mov_b32_e32 v147, v1
	v_lshlrev_b64 v[130:131], 21, v[130:131]
	v_lshl_add_u64 v[130:131], s[90:91], 0, v[130:131]
	v_lshlrev_b64 v[132:133], 6, v[146:147]
	v_lshl_add_u64 v[130:131], v[130:131], 0, v[132:133]
	v_lshl_add_u64 v[164:165], v[130:131], 0, v[0:1]
	v_ashrrev_i32_e32 v149, 31, v148
	v_lshlrev_b64 v[130:131], 2, v[148:149]
	v_lshl_add_u64 v[132:133], s[16:17], 0, v[130:131]
	v_lshl_add_u64 v[156:157], s[18:19], 0, v[130:131]
	global_load_dwordx4 v[130:133], v[132:133], off
	s_nop 0
	global_load_dwordx4 v[156:159], v[156:157], off
	v_lshlrev_b32_e32 v160, 4, v160
	v_lshl_or_b32 v161, v155, 3, v237
	v_mad_u32_u24 v155, v155, s94, v160
	ds_read_b64 v[172:173], v161
	ds_read_b128 v[160:163], v155
	s_and_b64 vcc, exec, s[0:1]
	v_mov_b64_e32 v[170:171], v[188:189]
	v_lshlrev_b32_e32 v174, 16, v170
	v_and_b32_e32 v175, 0xffff0000, v170
	v_lshlrev_b32_e32 v170, 16, v171
	v_and_b32_e32 v171, 0xffff0000, v171
	s_waitcnt lgkmcnt(0)
	v_pk_fma_f32 v[160:161], v[174:175], s[2:3], v[160:161] op_sel_hi:[1,0,1]
	v_pk_fma_f32 v[162:163], v[170:171], s[2:3], v[162:163] op_sel_hi:[1,0,1]
	v_pk_add_f32 v[160:161], v[160:161], v[172:173] op_sel_hi:[1,0] neg_lo:[0,1] neg_hi:[0,1]
	v_pk_add_f32 v[162:163], v[162:163], v[172:173] op_sel_hi:[1,0] neg_lo:[0,1] neg_hi:[0,1]
	v_pk_mul_f32 v[160:161], v[172:173], v[160:161] op_sel:[1,0]
	v_pk_mul_f32 v[162:163], v[172:173], v[162:163] op_sel:[1,0]
	s_waitcnt vmcnt(0)
	v_pk_fma_f32 v[130:131], v[130:131], v[160:161], v[156:157]
	v_pk_fma_f32 v[132:133], v[132:133], v[162:163], v[158:159]
	v_cvt_pk_bf16_f32 v156, v130, v131
	v_cvt_pk_bf16_f32 v157, v132, v133
	global_store_dwordx2 v[164:165], v[156:157], off
	s_cbranch_vccnz .LBB0_1759
	v_lshlrev_b64 v[146:147], 12, v[146:147]
	v_lshl_add_u64 v[146:147], s[20:21], 0, v[146:147]
	v_lshl_add_u64 v[146:147], v[148:149], 2, v[146:147]
	global_store_dwordx4 v[146:147], v[130:133], off
.LBB0_1759:
	s_nop 1
	v_add_u32_e32 v130, 0x200, v135
	v_bfe_u32 v155, v130, 3, 7
	v_ashrrev_i32_e32 v130, 7, v130
	v_and_or_b32 v160, v130, -8, v151
	v_lshlrev_b32_e32 v148, 2, v160
	v_add_u32_e32 v130, s39, v148
	v_ashrrev_i32_e32 v130, 5, v130
	v_ashrrev_i32_e32 v131, 31, v130
	v_or_b32_e32 v146, s40, v155
	v_mov_b32_e32 v147, v1
	v_lshlrev_b64 v[130:131], 21, v[130:131]
	v_lshl_add_u64 v[130:131], s[90:91], 0, v[130:131]
	v_lshlrev_b64 v[132:133], 6, v[146:147]
	v_lshl_add_u64 v[130:131], v[130:131], 0, v[132:133]
	v_lshl_add_u64 v[164:165], v[130:131], 0, v[0:1]
	v_ashrrev_i32_e32 v149, 31, v148
	v_lshlrev_b64 v[130:131], 2, v[148:149]
	v_lshl_add_u64 v[132:133], s[16:17], 0, v[130:131]
	v_lshl_add_u64 v[156:157], s[18:19], 0, v[130:131]
	global_load_dwordx4 v[130:133], v[132:133], off
	s_nop 0
	global_load_dwordx4 v[156:159], v[156:157], off
	v_lshlrev_b32_e32 v160, 4, v160
	v_lshl_or_b32 v161, v155, 3, v237
	v_mad_u32_u24 v155, v155, s94, v160
	ds_read_b64 v[172:173], v161
	ds_read_b128 v[160:163], v155
	s_and_b64 vcc, exec, s[0:1]
	v_mov_b64_e32 v[170:171], v[190:191]
	v_lshlrev_b32_e32 v174, 16, v170
	v_and_b32_e32 v175, 0xffff0000, v170
	v_lshlrev_b32_e32 v170, 16, v171
	v_and_b32_e32 v171, 0xffff0000, v171
	s_waitcnt lgkmcnt(0)
	v_pk_fma_f32 v[160:161], v[174:175], s[2:3], v[160:161] op_sel_hi:[1,0,1]
	v_pk_fma_f32 v[162:163], v[170:171], s[2:3], v[162:163] op_sel_hi:[1,0,1]
	v_pk_add_f32 v[160:161], v[160:161], v[172:173] op_sel_hi:[1,0] neg_lo:[0,1] neg_hi:[0,1]
	v_pk_add_f32 v[162:163], v[162:163], v[172:173] op_sel_hi:[1,0] neg_lo:[0,1] neg_hi:[0,1]
	v_pk_mul_f32 v[160:161], v[172:173], v[160:161] op_sel:[1,0]
	v_pk_mul_f32 v[162:163], v[172:173], v[162:163] op_sel:[1,0]
	s_waitcnt vmcnt(0)
	v_pk_fma_f32 v[130:131], v[130:131], v[160:161], v[156:157]
	v_pk_fma_f32 v[132:133], v[132:133], v[162:163], v[158:159]
	v_cvt_pk_bf16_f32 v156, v130, v131
	v_cvt_pk_bf16_f32 v157, v132, v133
	global_store_dwordx2 v[164:165], v[156:157], off
	s_cbranch_vccnz .LBB0_1761
	v_lshlrev_b64 v[146:147], 12, v[146:147]
	v_lshl_add_u64 v[146:147], s[20:21], 0, v[146:147]
	v_lshl_add_u64 v[146:147], v[148:149], 2, v[146:147]
	global_store_dwordx4 v[146:147], v[130:133], off
.LBB0_1761:
	s_nop 1
	v_add_u32_e32 v130, 0x300, v135
	v_bfe_u32 v135, v130, 3, 7
	v_ashrrev_i32_e32 v130, 7, v130
	v_and_or_b32 v155, v130, -8, v151
	v_lshlrev_b32_e32 v148, 2, v155
	v_add_u32_e32 v130, s39, v148
	v_ashrrev_i32_e32 v130, 5, v130
	v_ashrrev_i32_e32 v131, 31, v130
	v_or_b32_e32 v146, s40, v135
	v_mov_b32_e32 v147, v1
	v_lshlrev_b64 v[130:131], 21, v[130:131]
	v_lshl_add_u64 v[130:131], s[90:91], 0, v[130:131]
	v_lshlrev_b64 v[132:133], 6, v[146:147]
	v_lshl_add_u64 v[130:131], v[130:131], 0, v[132:133]
	v_lshl_add_u64 v[164:165], v[130:131], 0, v[0:1]
	v_ashrrev_i32_e32 v149, 31, v148
	v_lshlrev_b64 v[130:131], 2, v[148:149]
	v_lshl_add_u64 v[132:133], s[16:17], 0, v[130:131]
	v_lshl_add_u64 v[156:157], s[18:19], 0, v[130:131]
	global_load_dwordx4 v[130:133], v[132:133], off
	s_nop 0
	global_load_dwordx4 v[156:159], v[156:157], off
	v_lshlrev_b32_e32 v155, 4, v155
	v_lshl_or_b32 v160, v135, 3, v237
	v_mad_u32_u24 v135, v135, s94, v155
	ds_read_b64 v[172:173], v160
	ds_read_b128 v[160:163], v135
	s_and_b64 vcc, exec, s[0:1]
	v_mov_b64_e32 v[170:171], v[192:193]
	v_mov_b64_e32 v[186:187], v[194:195]
	v_mov_b64_e32 v[188:189], v[196:197]
	v_mov_b64_e32 v[190:191], v[198:199]
	v_mov_b64_e32 v[192:193], v[200:201]
	v_lshlrev_b32_e32 v174, 16, v170
	v_and_b32_e32 v175, 0xffff0000, v170
	v_lshlrev_b32_e32 v170, 16, v171
	v_and_b32_e32 v171, 0xffff0000, v171
	s_waitcnt lgkmcnt(0)
	v_pk_fma_f32 v[160:161], v[174:175], s[2:3], v[160:161] op_sel_hi:[1,0,1]
	v_pk_fma_f32 v[162:163], v[170:171], s[2:3], v[162:163] op_sel_hi:[1,0,1]
	v_pk_add_f32 v[160:161], v[160:161], v[172:173] op_sel_hi:[1,0] neg_lo:[0,1] neg_hi:[0,1]
	v_pk_add_f32 v[162:163], v[162:163], v[172:173] op_sel_hi:[1,0] neg_lo:[0,1] neg_hi:[0,1]
	v_pk_mul_f32 v[160:161], v[172:173], v[160:161] op_sel:[1,0]
	v_pk_mul_f32 v[162:163], v[172:173], v[162:163] op_sel:[1,0]
	s_waitcnt vmcnt(0)
	v_pk_fma_f32 v[130:131], v[130:131], v[160:161], v[156:157]
	v_pk_fma_f32 v[132:133], v[132:133], v[162:163], v[158:159]
	v_cvt_pk_bf16_f32 v156, v130, v131
	v_cvt_pk_bf16_f32 v157, v132, v133
	global_store_dwordx2 v[164:165], v[156:157], off
	s_cbranch_vccnz .LBB0_1754
	v_lshlrev_b64 v[146:147], 12, v[146:147]
	v_lshl_add_u64 v[146:147], s[20:21], 0, v[146:147]
	v_lshl_add_u64 v[146:147], v[148:149], 2, v[146:147]
	global_store_dwordx4 v[146:147], v[130:133], off
	s_branch .LBB0_1754

.LBB0_1767:
	v_add_u32_e32 v18, s22, v134
	v_ashrrev_i32_e32 v2, 7, v18
	v_and_or_b32 v19, v2, -8, v151
	v_lshlrev_b32_e32 v14, 2, v19
	v_add_u32_e32 v2, s39, v14
	v_ashrrev_i32_e32 v2, 5, v2
	v_ashrrev_i32_e32 v3, 31, v2
	v_lshlrev_b64 v[2:3], 21, v[2:3]
	v_lshl_add_u64 v[2:3], v[8:9], 0, v[2:3]
	v_lshl_add_u64 v[16:17], v[2:3], 0, v[0:1]
	s_and_b32 s32, s22, 0x7ff
	s_cbranch_scc1 .Lrx_skip1
	global_load_dwordx2 v[186:187], v[16:17], off
	global_load_dwordx2 v[188:189], v[16:17], off offset:2048
	s_mov_b64 s[100:101], 0x1000
	v_lshl_add_u64 v[190:191], v[16:17], 0, s[100:101]
	global_load_dwordx2 v[192:193], v[190:191], off offset:2048
	global_load_dwordx2 v[190:191], v[190:191], off
	s_mov_b64 s[100:101], 0x200000
	v_lshl_add_u64 v[194:195], v[16:17], 0, s[100:101]
	s_mov_b64 s[100:101], 0x201000
	v_lshl_add_u64 v[198:199], v[16:17], 0, s[100:101]
	global_load_dwordx2 v[196:197], v[194:195], off offset:2048
	global_load_dwordx2 v[194:195], v[194:195], off
	global_load_dwordx2 v[200:201], v[198:199], off offset:2048
	global_load_dwordx2 v[198:199], v[198:199], off
	s_waitcnt vmcnt(0)
.Lrx_skip1:
	v_ashrrev_i32_e32 v15, 31, v14
	v_lshlrev_b64 v[2:3], 2, v[14:15]
	v_lshl_add_u64 v[4:5], s[16:17], 0, v[2:3]
	v_lshl_add_u64 v[20:21], s[18:19], 0, v[2:3]
	global_load_dwordx4 v[2:5], v[4:5], off
	s_nop 0
	global_load_dwordx4 v[20:23], v[20:21], off
	v_lshl_add_u32 v19, v19, 4, v152
	ds_read_b128 v[24:27], v19
	s_and_b64 vcc, exec, s[0:1]
	v_mov_b64_e32 v[28:29], v[186:187]
	v_lshlrev_b32_e32 v30, 16, v28
	v_and_b32_e32 v31, 0xffff0000, v28
	v_lshlrev_b32_e32 v28, 16, v29
	v_and_b32_e32 v29, 0xffff0000, v29
	s_waitcnt lgkmcnt(0)
	v_pk_fma_f32 v[24:25], v[30:31], s[2:3], v[24:25] op_sel_hi:[1,0,1]
	v_pk_fma_f32 v[26:27], v[28:29], s[2:3], v[26:27] op_sel_hi:[1,0,1]
	v_pk_add_f32 v[24:25], v[24:25], v[10:11] neg_lo:[0,1] neg_hi:[0,1]
	v_pk_add_f32 v[26:27], v[26:27], v[10:11] neg_lo:[0,1] neg_hi:[0,1]
	v_pk_mul_f32 v[24:25], v[6:7], v[24:25]
	v_pk_mul_f32 v[26:27], v[6:7], v[26:27]
	s_waitcnt vmcnt(0)
	v_pk_fma_f32 v[2:3], v[2:3], v[24:25], v[20:21]
	v_pk_fma_f32 v[4:5], v[4:5], v[26:27], v[22:23]
	v_cvt_pk_bf16_f32 v20, v2, v3
	v_cvt_pk_bf16_f32 v21, v4, v5
	global_store_dwordx2 v[16:17], v[20:21], off
	s_cbranch_vccnz .LBB0_1769
	v_lshl_add_u64 v[14:15], v[14:15], 2, v[12:13]
	global_store_dwordx4 v[14:15], v[2:5], off
.LBB0_1769:
	s_nop 1
	v_add_u32_e32 v2, 0x100, v18
	v_bfe_u32 v19, v2, 3, 7
	v_ashrrev_i32_e32 v2, 7, v2
	v_and_or_b32 v24, v2, -8, v151
	v_lshlrev_b32_e32 v16, 2, v24
	v_add_u32_e32 v2, s39, v16
	v_ashrrev_i32_e32 v2, 5, v2
	v_ashrrev_i32_e32 v3, 31, v2
	v_or_b32_e32 v14, s41, v19
	v_mov_b32_e32 v15, v1
	v_lshlrev_b64 v[2:3], 21, v[2:3]
	v_lshl_add_u64 v[2:3], s[90:91], 0, v[2:3]
	v_lshlrev_b64 v[4:5], 6, v[14:15]
	v_lshl_add_u64 v[2:3], v[2:3], 0, v[4:5]
	v_lshl_add_u64 v[28:29], v[2:3], 0, v[0:1]
	v_ashrrev_i32_e32 v17, 31, v16
	v_lshlrev_b64 v[2:3], 2, v[16:17]
	v_lshl_add_u64 v[4:5], s[16:17], 0, v[2:3]
	v_lshl_add_u64 v[20:21], s[18:19], 0, v[2:3]
	global_load_dwordx4 v[2:5], v[4:5], off
	s_nop 0
	global_load_dwordx4 v[20:23], v[20:21], off
	v_lshlrev_b32_e32 v24, 4, v24
	v_lshl_or_b32 v25, v19, 3, v238
	v_mad_u32_u24 v19, v19, s94, v24
	ds_read_b64 v[32:33], v25
	ds_read_b128 v[24:27], v19
	s_and_b64 vcc, exec, s[0:1]
	v_mov_b64_e32 v[30:31], v[188:189]
	v_lshlrev_b32_e32 v34, 16, v30
	v_and_b32_e32 v35, 0xffff0000, v30
	v_lshlrev_b32_e32 v30, 16, v31
	v_and_b32_e32 v31, 0xffff0000, v31
	s_waitcnt lgkmcnt(0)
	v_pk_fma_f32 v[24:25], v[34:35], s[2:3], v[24:25] op_sel_hi:[1,0,1]
	v_pk_fma_f32 v[26:27], v[30:31], s[2:3], v[26:27] op_sel_hi:[1,0,1]
	v_pk_add_f32 v[24:25], v[24:25], v[32:33] op_sel_hi:[1,0] neg_lo:[0,1] neg_hi:[0,1]
	v_pk_add_f32 v[26:27], v[26:27], v[32:33] op_sel_hi:[1,0] neg_lo:[0,1] neg_hi:[0,1]
	v_pk_mul_f32 v[24:25], v[32:33], v[24:25] op_sel:[1,0]
	v_pk_mul_f32 v[26:27], v[32:33], v[26:27] op_sel:[1,0]
	s_waitcnt vmcnt(0)
	v_pk_fma_f32 v[2:3], v[2:3], v[24:25], v[20:21]
	v_pk_fma_f32 v[4:5], v[4:5], v[26:27], v[22:23]
	v_cvt_pk_bf16_f32 v20, v2, v3
	v_cvt_pk_bf16_f32 v21, v4, v5
	global_store_dwordx2 v[28:29], v[20:21], off
	s_cbranch_vccnz .LBB0_1771
	v_lshlrev_b64 v[14:15], 12, v[14:15]
	v_lshl_add_u64 v[14:15], s[20:21], 0, v[14:15]
	v_lshl_add_u64 v[14:15], v[16:17], 2, v[14:15]
	global_store_dwordx4 v[14:15], v[2:5], off
.LBB0_1771:
	s_nop 1
	v_add_u32_e32 v2, 0x200, v18
	v_bfe_u32 v19, v2, 3, 7
	v_ashrrev_i32_e32 v2, 7, v2
	v_and_or_b32 v24, v2, -8, v151
	v_lshlrev_b32_e32 v16, 2, v24
	v_add_u32_e32 v2, s39, v16
	v_ashrrev_i32_e32 v2, 5, v2
	v_ashrrev_i32_e32 v3, 31, v2
	v_or_b32_e32 v14, s41, v19
	v_mov_b32_e32 v15, v1
	v_lshlrev_b64 v[2:3], 21, v[2:3]
	v_lshl_add_u64 v[2:3], s[90:91], 0, v[2:3]
	v_lshlrev_b64 v[4:5], 6, v[14:15]
	v_lshl_add_u64 v[2:3], v[2:3], 0, v[4:5]
	v_lshl_add_u64 v[28:29], v[2:3], 0, v[0:1]
	v_ashrrev_i32_e32 v17, 31, v16
	v_lshlrev_b64 v[2:3], 2, v[16:17]
	v_lshl_add_u64 v[4:5], s[16:17], 0, v[2:3]
	v_lshl_add_u64 v[20:21], s[18:19], 0, v[2:3]
	global_load_dwordx4 v[2:5], v[4:5], off
	s_nop 0
	global_load_dwordx4 v[20:23], v[20:21], off
	v_lshlrev_b32_e32 v24, 4, v24
	v_lshl_or_b32 v25, v19, 3, v238
	v_mad_u32_u24 v19, v19, s94, v24
	ds_read_b64 v[32:33], v25
	ds_read_b128 v[24:27], v19
	s_and_b64 vcc, exec, s[0:1]
	v_mov_b64_e32 v[30:31], v[190:191]
	v_lshlrev_b32_e32 v34, 16, v30
	v_and_b32_e32 v35, 0xffff0000, v30
	v_lshlrev_b32_e32 v30, 16, v31
	v_and_b32_e32 v31, 0xffff0000, v31
	s_waitcnt lgkmcnt(0)
	v_pk_fma_f32 v[24:25], v[34:35], s[2:3], v[24:25] op_sel_hi:[1,0,1]
	v_pk_fma_f32 v[26:27], v[30:31], s[2:3], v[26:27] op_sel_hi:[1,0,1]
	v_pk_add_f32 v[24:25], v[24:25], v[32:33] op_sel_hi:[1,0] neg_lo:[0,1] neg_hi:[0,1]
	v_pk_add_f32 v[26:27], v[26:27], v[32:33] op_sel_hi:[1,0] neg_lo:[0,1] neg_hi:[0,1]
	v_pk_mul_f32 v[24:25], v[32:33], v[24:25] op_sel:[1,0]
	v_pk_mul_f32 v[26:27], v[32:33], v[26:27] op_sel:[1,0]
	s_waitcnt vmcnt(0)
	v_pk_fma_f32 v[2:3], v[2:3], v[24:25], v[20:21]
	v_pk_fma_f32 v[4:5], v[4:5], v[26:27], v[22:23]
	v_cvt_pk_bf16_f32 v20, v2, v3
	v_cvt_pk_bf16_f32 v21, v4, v5
	global_store_dwordx2 v[28:29], v[20:21], off
	s_cbranch_vccnz .LBB0_1773
	v_lshlrev_b64 v[14:15], 12, v[14:15]
	v_lshl_add_u64 v[14:15], s[20:21], 0, v[14:15]
	v_lshl_add_u64 v[14:15], v[16:17], 2, v[14:15]
	global_store_dwordx4 v[14:15], v[2:5], off
.LBB0_1773:
	s_nop 1
	v_add_u32_e32 v2, 0x300, v18
	v_bfe_u32 v22, v2, 3, 7
	v_ashrrev_i32_e32 v2, 7, v2
	v_and_or_b32 v23, v2, -8, v151
	v_lshlrev_b32_e32 v16, 2, v23
	v_add_u32_e32 v2, s39, v16
	v_ashrrev_i32_e32 v2, 5, v2
	v_ashrrev_i32_e32 v3, 31, v2
	v_or_b32_e32 v14, s41, v22
	v_mov_b32_e32 v15, v1
	v_lshlrev_b64 v[2:3], 21, v[2:3]
	v_lshl_add_u64 v[2:3], s[90:91], 0, v[2:3]
	v_lshlrev_b64 v[4:5], 6, v[14:15]
	v_lshl_add_u64 v[2:3], v[2:3], 0, v[4:5]
	v_lshl_add_u64 v[26:27], v[2:3], 0, v[0:1]
	v_ashrrev_i32_e32 v17, 31, v16
	v_lshlrev_b64 v[2:3], 2, v[16:17]
	v_lshl_add_u64 v[4:5], s[16:17], 0, v[2:3]
	v_lshl_add_u64 v[18:19], s[18:19], 0, v[2:3]
	global_load_dwordx4 v[2:5], v[4:5], off
	s_nop 0
	global_load_dwordx4 v[18:21], v[18:19], off
	v_lshlrev_b32_e32 v23, 4, v23
	v_lshl_or_b32 v24, v22, 3, v238
	v_mad_u32_u24 v22, v22, s94, v23
	ds_read_b64 v[30:31], v24
	ds_read_b128 v[22:25], v22
	s_and_b64 vcc, exec, s[0:1]
	v_mov_b64_e32 v[28:29], v[192:193]
	v_mov_b64_e32 v[186:187], v[194:195]
	v_mov_b64_e32 v[188:189], v[196:197]
	v_mov_b64_e32 v[190:191], v[198:199]
	v_mov_b64_e32 v[192:193], v[200:201]
	v_lshlrev_b32_e32 v32, 16, v28
	v_and_b32_e32 v33, 0xffff0000, v28
	v_lshlrev_b32_e32 v28, 16, v29
	v_and_b32_e32 v29, 0xffff0000, v29
	s_waitcnt lgkmcnt(0)
	v_pk_fma_f32 v[22:23], v[32:33], s[2:3], v[22:23] op_sel_hi:[1,0,1]
	v_pk_fma_f32 v[24:25], v[28:29], s[2:3], v[24:25] op_sel_hi:[1,0,1]
	v_pk_add_f32 v[22:23], v[22:23], v[30:31] op_sel_hi:[1,0] neg_lo:[0,1] neg_hi:[0,1]
	v_pk_add_f32 v[24:25], v[24:25], v[30:31] op_sel_hi:[1,0] neg_lo:[0,1] neg_hi:[0,1]
	v_pk_mul_f32 v[22:23], v[30:31], v[22:23] op_sel:[1,0]
	v_pk_mul_f32 v[24:25], v[30:31], v[24:25] op_sel:[1,0]
	s_waitcnt vmcnt(0)
	v_pk_fma_f32 v[2:3], v[2:3], v[22:23], v[18:19]
	v_pk_fma_f32 v[4:5], v[4:5], v[24:25], v[20:21]
	v_cvt_pk_bf16_f32 v18, v2, v3
	v_cvt_pk_bf16_f32 v19, v4, v5
	global_store_dwordx2 v[26:27], v[18:19], off
	s_cbranch_vccnz .LBB0_1766
	v_lshlrev_b64 v[14:15], 12, v[14:15]
	v_lshl_add_u64 v[14:15], s[20:21], 0, v[14:15]
	v_lshl_add_u64 v[14:15], v[16:17], 2, v[14:15]
	global_store_dwordx4 v[14:15], v[2:5], off
	s_branch .LBB0_1766
